# QC full stack with per-block early-barrier tails: 2 MFMAs after the ai=0 block, 6 after the ai=1 block
# speedup vs baseline: 1.0061x; 1.0061x over previous
.LBB0_115:
	ds_read_b128 v[148:151], v154
	ds_read_b128 v[158:161], v154 offset:1024
	ds_read_b128 v[162:165], v154 offset:2048
	ds_read_b128 v[166:169], v154 offset:3072
	ds_read_b128 v[170:173], v155
	ds_read_b128 v[174:177], v155 offset:1024
	ds_read_b128 v[178:181], v155 offset:2048
	ds_read_b128 v[182:185], v155 offset:3072
	s_add_u32 s46, s44, 0xfff00080
	s_addc_u32 s47, s45, -1
	s_cmp_eq_u32 s69, 60
	s_cselect_b32 s49, s35, s47
	s_cselect_b32 s48, s43, s46
	s_cselect_b32 s47, s37, s68
	s_cselect_b32 s46, s66, s67
	v_lshl_add_u64 v[218:219], s[44:45], 0, v[140:141]
	s_add_i32 m0, s54, 0xc000
	ds_read_b128 v[186:189], v156
	ds_read_b128 v[190:193], v156 offset:1024
	ds_read_b128 v[194:197], v156 offset:2048
	ds_read_b128 v[198:201], v156 offset:3072
	ds_read_b128 v[202:205], v156 offset:4096
	ds_read_b128 v[206:209], v156 offset:5120
	ds_read_b128 v[210:213], v156 offset:6144
	ds_read_b128 v[214:217], v156 offset:7168
	global_load_lds_dwordx4 v[218:219], off
	v_lshl_add_u64 v[218:219], s[44:45], 0, v[142:143]
	s_add_i32 m0, s54, 0xe000
	s_nop 0
	global_load_lds_dwordx4 v[218:219], off
	s_waitcnt vmcnt(8)
	s_waitcnt lgkmcnt(0)
	s_barrier
	s_setprio 1
	s_waitcnt lgkmcnt(0)
	v_mfma_f32_16x16x32_bf16 v[126:129], v[148:151], v[186:189], v[126:129]
	v_mfma_f32_16x16x32_bf16 v[122:125], v[162:165], v[186:189], v[122:125]
	v_mfma_f32_16x16x32_bf16 v[118:121], v[148:151], v[194:197], v[118:121]
	v_mfma_f32_16x16x32_bf16 v[110:113], v[162:165], v[194:197], v[110:113]
	v_mfma_f32_16x16x32_bf16 v[102:105], v[148:151], v[202:205], v[102:105]
	v_mfma_f32_16x16x32_bf16 v[94:97], v[162:165], v[202:205], v[94:97]
	v_mfma_f32_16x16x32_bf16 v[86:89], v[148:151], v[210:213], v[86:89]
	v_mfma_f32_16x16x32_bf16 v[78:81], v[162:165], v[210:213], v[78:81]
	v_mfma_f32_16x16x32_bf16 v[126:129], v[158:161], v[190:193], v[126:129]
	v_mfma_f32_16x16x32_bf16 v[122:125], v[166:169], v[190:193], v[122:125]
	v_mfma_f32_16x16x32_bf16 v[118:121], v[158:161], v[198:201], v[118:121]
	v_mfma_f32_16x16x32_bf16 v[110:113], v[166:169], v[198:201], v[110:113]
	v_mfma_f32_16x16x32_bf16 v[102:105], v[158:161], v[206:209], v[102:105]
	v_mfma_f32_16x16x32_bf16 v[94:97], v[166:169], v[206:209], v[94:97]
	v_mfma_f32_16x16x32_bf16 v[86:89], v[158:161], v[214:217], v[86:89]
	v_mfma_f32_16x16x32_bf16 v[78:81], v[166:169], v[214:217], v[78:81]
	s_setprio 0
	s_setprio 1
	v_mfma_f32_16x16x32_bf16 v[114:117], v[170:173], v[186:189], v[114:117]
	v_mfma_f32_16x16x32_bf16 v[106:109], v[178:181], v[186:189], v[106:109]
	v_mfma_f32_16x16x32_bf16 v[98:101], v[170:173], v[194:197], v[98:101]
	v_mfma_f32_16x16x32_bf16 v[90:93], v[178:181], v[194:197], v[90:93]
	v_mfma_f32_16x16x32_bf16 v[82:85], v[170:173], v[202:205], v[82:85]
	v_mfma_f32_16x16x32_bf16 v[74:77], v[178:181], v[202:205], v[74:77]
	v_mfma_f32_16x16x32_bf16 v[70:73], v[170:173], v[210:213], v[70:73]
	v_mfma_f32_16x16x32_bf16 v[66:69], v[178:181], v[210:213], v[66:69]
	v_mfma_f32_16x16x32_bf16 v[114:117], v[174:177], v[190:193], v[114:117]
	v_mfma_f32_16x16x32_bf16 v[106:109], v[182:185], v[190:193], v[106:109]
	v_mfma_f32_16x16x32_bf16 v[98:101], v[174:177], v[198:201], v[98:101]
	v_mfma_f32_16x16x32_bf16 v[90:93], v[182:185], v[198:201], v[90:93]
	v_mfma_f32_16x16x32_bf16 v[82:85], v[174:177], v[206:209], v[82:85]
	v_mfma_f32_16x16x32_bf16 v[74:77], v[182:185], v[206:209], v[74:77]
	s_setprio 3
	s_barrier
	v_mfma_f32_16x16x32_bf16 v[70:73], v[174:177], v[214:217], v[70:73]
	v_mfma_f32_16x16x32_bf16 v[66:69], v[182:185], v[214:217], v[66:69]
	s_setprio 0
	s_add_i32 s70, s64, s51
	v_lshl_add_u64 v[218:219], s[46:47], 0, v[134:135]
	s_mov_b32 m0, s70
	ds_read_b128 v[186:189], v156 offset:16384
	ds_read_b128 v[190:193], v156 offset:17408
	ds_read_b128 v[194:197], v156 offset:18432
	ds_read_b128 v[198:201], v156 offset:19456
	ds_read_b128 v[202:205], v156 offset:20480
	ds_read_b128 v[206:209], v156 offset:21504
	ds_read_b128 v[210:213], v156 offset:22528
	ds_read_b128 v[214:217], v156 offset:23552
	global_load_lds_dwordx4 v[218:219], off
	s_add_i32 m0, s70, 0x2000
	s_add_u32 s70, s46, 0x100000
	v_lshl_add_u64 v[220:221], s[46:47], 0, v[130:131]
	s_addc_u32 s71, s47, 0
	s_add_i32 s72, s65, s51
	global_load_lds_dwordx4 v[220:221], off
	v_lshl_add_u64 v[222:223], s[70:71], 0, v[134:135]
	s_mov_b32 m0, s72
	v_lshl_add_u64 v[224:225], s[48:49], 0, v[132:133]
	global_load_lds_dwordx4 v[222:223], off
	v_lshl_add_u64 v[222:223], s[70:71], 0, v[130:131]
	s_add_i32 m0, s72, 0x2000
	s_nop 0
	global_load_lds_dwordx4 v[222:223], off
	v_lshl_add_u64 v[222:223], s[48:49], 0, v[136:137]
	s_mov_b32 m0, s54
	s_nop 0
	global_load_lds_dwordx4 v[222:223], off
	s_mov_b32 m0, s55
	s_nop 0
	global_load_lds_dwordx4 v[224:225], off
	s_waitcnt vmcnt(8)
	s_waitcnt lgkmcnt(0)
	s_barrier
	s_setprio 1
	s_waitcnt lgkmcnt(0)
	v_mfma_f32_16x16x32_bf16 v[62:65], v[148:151], v[186:189], v[62:65]
	v_mfma_f32_16x16x32_bf16 v[58:61], v[162:165], v[186:189], v[58:61]
	v_mfma_f32_16x16x32_bf16 v[54:57], v[148:151], v[194:197], v[54:57]
	v_mfma_f32_16x16x32_bf16 v[46:49], v[162:165], v[194:197], v[46:49]
	v_mfma_f32_16x16x32_bf16 v[38:41], v[148:151], v[202:205], v[38:41]
	v_mfma_f32_16x16x32_bf16 v[30:33], v[162:165], v[202:205], v[30:33]
	v_mfma_f32_16x16x32_bf16 v[22:25], v[148:151], v[210:213], v[22:25]
	v_mfma_f32_16x16x32_bf16 v[14:17], v[162:165], v[210:213], v[14:17]
	v_mfma_f32_16x16x32_bf16 v[62:65], v[158:161], v[190:193], v[62:65]
	v_mfma_f32_16x16x32_bf16 v[58:61], v[166:169], v[190:193], v[58:61]
	v_mfma_f32_16x16x32_bf16 v[54:57], v[158:161], v[198:201], v[54:57]
	v_mfma_f32_16x16x32_bf16 v[46:49], v[166:169], v[198:201], v[46:49]
	v_mfma_f32_16x16x32_bf16 v[38:41], v[158:161], v[206:209], v[38:41]
	v_mfma_f32_16x16x32_bf16 v[30:33], v[166:169], v[206:209], v[30:33]
	v_mfma_f32_16x16x32_bf16 v[22:25], v[158:161], v[214:217], v[22:25]
	v_mfma_f32_16x16x32_bf16 v[14:17], v[166:169], v[214:217], v[14:17]
	s_setprio 0
	s_setprio 1
	v_mfma_f32_16x16x32_bf16 v[50:53], v[170:173], v[186:189], v[50:53]
	v_mfma_f32_16x16x32_bf16 v[42:45], v[178:181], v[186:189], v[42:45]
	v_mfma_f32_16x16x32_bf16 v[34:37], v[170:173], v[194:197], v[34:37]
	v_mfma_f32_16x16x32_bf16 v[26:29], v[178:181], v[194:197], v[26:29]
	v_mfma_f32_16x16x32_bf16 v[18:21], v[170:173], v[202:205], v[18:21]
	v_mfma_f32_16x16x32_bf16 v[10:13], v[178:181], v[202:205], v[10:13]
	v_mfma_f32_16x16x32_bf16 v[6:9], v[170:173], v[210:213], v[6:9]
	v_mfma_f32_16x16x32_bf16 v[2:5], v[178:181], v[210:213], v[2:5]
	v_mfma_f32_16x16x32_bf16 v[50:53], v[174:177], v[190:193], v[50:53]
	v_mfma_f32_16x16x32_bf16 v[42:45], v[182:185], v[190:193], v[42:45]
	s_setprio 3
	s_barrier
	v_mfma_f32_16x16x32_bf16 v[34:37], v[174:177], v[198:201], v[34:37]
	v_mfma_f32_16x16x32_bf16 v[26:29], v[182:185], v[198:201], v[26:29]
	v_mfma_f32_16x16x32_bf16 v[18:21], v[174:177], v[206:209], v[18:21]
	v_mfma_f32_16x16x32_bf16 v[10:13], v[182:185], v[206:209], v[10:13]
	v_mfma_f32_16x16x32_bf16 v[6:9], v[174:177], v[214:217], v[6:9]
	v_mfma_f32_16x16x32_bf16 v[2:5], v[182:185], v[214:217], v[2:5]
	s_setprio 0
	s_add_i32 s70, 0, 0x18000
	v_add_u32_e32 v138, s70, v152
	s_add_i32 s71, 0, 0x1c000
	ds_read_b128 v[148:151], v138
	ds_read_b128 v[158:161], v138 offset:1024
	ds_read_b128 v[162:165], v138 offset:2048
	ds_read_b128 v[166:169], v138 offset:3072
	v_add_u32_e32 v138, s71, v152
	ds_read_b128 v[170:173], v138
	ds_read_b128 v[174:177], v138 offset:1024
	ds_read_b128 v[178:181], v138 offset:2048
	ds_read_b128 v[182:185], v138 offset:3072
	s_add_u32 s48, s48, 0x100000
	s_addc_u32 s49, s49, 0
	s_mov_b32 m0, s56
	v_lshl_add_u64 v[226:227], s[48:49], 0, v[136:137]
	ds_read_b128 v[186:189], v156 offset:32768
	ds_read_b128 v[190:193], v156 offset:33792
	ds_read_b128 v[194:197], v156 offset:34816
	ds_read_b128 v[198:201], v156 offset:35840
	ds_read_b128 v[202:205], v156 offset:36864
	ds_read_b128 v[206:209], v156 offset:37888
	ds_read_b128 v[210:213], v156 offset:38912
	ds_read_b128 v[214:217], v156 offset:39936
	global_load_lds_dwordx4 v[226:227], off
	v_lshl_add_u64 v[226:227], s[48:49], 0, v[132:133]
	s_mov_b32 m0, s57
	s_nop 0
	global_load_lds_dwordx4 v[226:227], off
	s_waitcnt vmcnt(8)
	s_waitcnt lgkmcnt(0)
	s_barrier
	s_setprio 1
	s_waitcnt lgkmcnt(0)
	v_mfma_f32_16x16x32_bf16 v[126:129], v[148:151], v[186:189], v[126:129]
	v_mfma_f32_16x16x32_bf16 v[122:125], v[162:165], v[186:189], v[122:125]
	v_mfma_f32_16x16x32_bf16 v[118:121], v[148:151], v[194:197], v[118:121]
	v_mfma_f32_16x16x32_bf16 v[110:113], v[162:165], v[194:197], v[110:113]
	v_mfma_f32_16x16x32_bf16 v[102:105], v[148:151], v[202:205], v[102:105]
	v_mfma_f32_16x16x32_bf16 v[94:97], v[162:165], v[202:205], v[94:97]
	v_mfma_f32_16x16x32_bf16 v[86:89], v[148:151], v[210:213], v[86:89]
	v_mfma_f32_16x16x32_bf16 v[78:81], v[162:165], v[210:213], v[78:81]
	v_mfma_f32_16x16x32_bf16 v[126:129], v[158:161], v[190:193], v[126:129]
	v_mfma_f32_16x16x32_bf16 v[122:125], v[166:169], v[190:193], v[122:125]
	v_mfma_f32_16x16x32_bf16 v[118:121], v[158:161], v[198:201], v[118:121]
	v_mfma_f32_16x16x32_bf16 v[110:113], v[166:169], v[198:201], v[110:113]
	v_mfma_f32_16x16x32_bf16 v[102:105], v[158:161], v[206:209], v[102:105]
	v_mfma_f32_16x16x32_bf16 v[94:97], v[166:169], v[206:209], v[94:97]
	v_mfma_f32_16x16x32_bf16 v[86:89], v[158:161], v[214:217], v[86:89]
	v_mfma_f32_16x16x32_bf16 v[78:81], v[166:169], v[214:217], v[78:81]
	s_setprio 0
	s_setprio 1
	v_mfma_f32_16x16x32_bf16 v[114:117], v[170:173], v[186:189], v[114:117]
	v_mfma_f32_16x16x32_bf16 v[106:109], v[178:181], v[186:189], v[106:109]
	v_mfma_f32_16x16x32_bf16 v[98:101], v[170:173], v[194:197], v[98:101]
	v_mfma_f32_16x16x32_bf16 v[90:93], v[178:181], v[194:197], v[90:93]
	v_mfma_f32_16x16x32_bf16 v[82:85], v[170:173], v[202:205], v[82:85]
	v_mfma_f32_16x16x32_bf16 v[74:77], v[178:181], v[202:205], v[74:77]
	v_mfma_f32_16x16x32_bf16 v[70:73], v[170:173], v[210:213], v[70:73]
	v_mfma_f32_16x16x32_bf16 v[66:69], v[178:181], v[210:213], v[66:69]
	v_mfma_f32_16x16x32_bf16 v[114:117], v[174:177], v[190:193], v[114:117]
	v_mfma_f32_16x16x32_bf16 v[106:109], v[182:185], v[190:193], v[106:109]
	v_mfma_f32_16x16x32_bf16 v[98:101], v[174:177], v[198:201], v[98:101]
	v_mfma_f32_16x16x32_bf16 v[90:93], v[182:185], v[198:201], v[90:93]
	v_mfma_f32_16x16x32_bf16 v[82:85], v[174:177], v[206:209], v[82:85]
	v_mfma_f32_16x16x32_bf16 v[74:77], v[182:185], v[206:209], v[74:77]
	s_setprio 3
	s_barrier
	v_mfma_f32_16x16x32_bf16 v[70:73], v[174:177], v[214:217], v[70:73]
	v_mfma_f32_16x16x32_bf16 v[66:69], v[182:185], v[214:217], v[66:69]
	s_setprio 0
	s_add_i32 s48, s70, s51
	v_lshl_add_u64 v[218:219], v[218:219], 0, s[28:29]
	s_mov_b32 m0, s48
	ds_read_b128 v[186:189], v156 offset:49152
	ds_read_b128 v[190:193], v156 offset:50176
	ds_read_b128 v[194:197], v156 offset:51200
	ds_read_b128 v[198:201], v156 offset:52224
	ds_read_b128 v[202:205], v156 offset:53248
	ds_read_b128 v[206:209], v156 offset:54272
	ds_read_b128 v[210:213], v156 offset:55296
	ds_read_b128 v[214:217], v156 offset:56320
	global_load_lds_dwordx4 v[218:219], off
	s_add_i32 m0, s48, 0x2000
	s_add_u32 s46, s46, 0x100080
	v_lshl_add_u64 v[218:219], v[220:221], 0, s[28:29]
	s_addc_u32 s47, s47, 0
	s_add_i32 s48, s71, s51
	global_load_lds_dwordx4 v[218:219], off
	v_lshl_add_u64 v[218:219], s[46:47], 0, v[134:135]
	s_mov_b32 m0, s48
	s_nop 0
	global_load_lds_dwordx4 v[218:219], off
	v_lshl_add_u64 v[218:219], s[46:47], 0, v[130:131]
	s_add_i32 m0, s48, 0x2000
	s_nop 0
	global_load_lds_dwordx4 v[218:219], off
	v_lshl_add_u64 v[218:219], v[222:223], 0, s[28:29]
	s_mov_b32 m0, s59
	s_nop 0
	global_load_lds_dwordx4 v[218:219], off
	v_lshl_add_u64 v[218:219], v[224:225], 0, s[28:29]
	s_mov_b32 m0, s60
	s_nop 0
	global_load_lds_dwordx4 v[218:219], off
	s_waitcnt vmcnt(8)
	s_waitcnt lgkmcnt(0)
	s_barrier
	s_setprio 1
	s_waitcnt lgkmcnt(0)
	v_mfma_f32_16x16x32_bf16 v[62:65], v[148:151], v[186:189], v[62:65]
	v_mfma_f32_16x16x32_bf16 v[58:61], v[162:165], v[186:189], v[58:61]
	v_mfma_f32_16x16x32_bf16 v[54:57], v[148:151], v[194:197], v[54:57]
	v_mfma_f32_16x16x32_bf16 v[46:49], v[162:165], v[194:197], v[46:49]
	v_mfma_f32_16x16x32_bf16 v[38:41], v[148:151], v[202:205], v[38:41]
	v_mfma_f32_16x16x32_bf16 v[30:33], v[162:165], v[202:205], v[30:33]
	v_mfma_f32_16x16x32_bf16 v[22:25], v[148:151], v[210:213], v[22:25]
	v_mfma_f32_16x16x32_bf16 v[14:17], v[162:165], v[210:213], v[14:17]
	v_mfma_f32_16x16x32_bf16 v[62:65], v[158:161], v[190:193], v[62:65]
	v_mfma_f32_16x16x32_bf16 v[58:61], v[166:169], v[190:193], v[58:61]
	v_mfma_f32_16x16x32_bf16 v[54:57], v[158:161], v[198:201], v[54:57]
	v_mfma_f32_16x16x32_bf16 v[46:49], v[166:169], v[198:201], v[46:49]
	v_mfma_f32_16x16x32_bf16 v[38:41], v[158:161], v[206:209], v[38:41]
	v_mfma_f32_16x16x32_bf16 v[30:33], v[166:169], v[206:209], v[30:33]
	v_mfma_f32_16x16x32_bf16 v[22:25], v[158:161], v[214:217], v[22:25]
	v_mfma_f32_16x16x32_bf16 v[14:17], v[166:169], v[214:217], v[14:17]
	s_setprio 0
	s_setprio 1
	v_mfma_f32_16x16x32_bf16 v[50:53], v[170:173], v[186:189], v[50:53]
	v_mfma_f32_16x16x32_bf16 v[42:45], v[178:181], v[186:189], v[42:45]
	v_mfma_f32_16x16x32_bf16 v[34:37], v[170:173], v[194:197], v[34:37]
	v_mfma_f32_16x16x32_bf16 v[26:29], v[178:181], v[194:197], v[26:29]
	v_mfma_f32_16x16x32_bf16 v[18:21], v[170:173], v[202:205], v[18:21]
	v_mfma_f32_16x16x32_bf16 v[10:13], v[178:181], v[202:205], v[10:13]
	v_mfma_f32_16x16x32_bf16 v[6:9], v[170:173], v[210:213], v[6:9]
	v_mfma_f32_16x16x32_bf16 v[2:5], v[178:181], v[210:213], v[2:5]
	v_mfma_f32_16x16x32_bf16 v[50:53], v[174:177], v[190:193], v[50:53]
	v_mfma_f32_16x16x32_bf16 v[42:45], v[182:185], v[190:193], v[42:45]
	s_setprio 3
	s_barrier
	v_mfma_f32_16x16x32_bf16 v[34:37], v[174:177], v[198:201], v[34:37]
	v_mfma_f32_16x16x32_bf16 v[26:29], v[182:185], v[198:201], v[26:29]
	v_mfma_f32_16x16x32_bf16 v[18:21], v[174:177], v[206:209], v[18:21]
	v_mfma_f32_16x16x32_bf16 v[10:13], v[182:185], v[206:209], v[10:13]
	v_mfma_f32_16x16x32_bf16 v[6:9], v[174:177], v[214:217], v[6:9]
	v_mfma_f32_16x16x32_bf16 v[2:5], v[182:185], v[214:217], v[2:5]
	s_setprio 0
	s_add_i32 s69, s69, 2
	s_add_u32 s44, s44, 0x100
	s_addc_u32 s45, s45, 0
	s_add_u32 s67, s67, 0x100
	s_addc_u32 s68, s68, 0
	s_cmp_gt_u32 s69, 61
	s_cbranch_scc0 .LBB0_115
	s_and_b64 vcc, exec, s[30:31]
	s_cbranch_vccz .LBB0_118
	s_barrier

.LBB0_540:
	v_add_u32_e32 v139, s64, v186
	ds_read_b128 v[130:133], v139
	ds_read_b128 v[134:137], v139 offset:1024
	ds_read_b128 v[146:149], v139 offset:2048
	ds_read_b128 v[150:153], v139 offset:3072
	v_add_u32_e32 v139, s65, v186
	s_add_u32 s48, s44, s46
	ds_read_b128 v[154:157], v139
	ds_read_b128 v[174:177], v139 offset:1024
	ds_read_b128 v[178:181], v139 offset:2048
	ds_read_b128 v[182:185], v139 offset:3072
	s_addc_u32 s49, s45, s47
	s_add_u32 s48, s48, 0x100
	s_addc_u32 s49, s49, 0
	s_add_u32 s71, s68, s46
	s_addc_u32 s72, s69, s47
	s_cmpk_eq_i32 s46, 0x1f00
	s_cselect_b32 s51, s39, s49
	s_cselect_b32 s50, s66, s48
	s_cselect_b32 s49, s37, s72
	s_cselect_b32 s48, s67, s71
	v_lshl_add_u64 v[222:223], v[142:143], 0, s[46:47]
	s_add_i32 m0, s55, 0xc000
	ds_read_b128 v[190:193], v188
	ds_read_b128 v[194:197], v188 offset:1024
	ds_read_b128 v[198:201], v188 offset:2048
	ds_read_b128 v[202:205], v188 offset:3072
	ds_read_b128 v[206:209], v188 offset:4096
	ds_read_b128 v[210:213], v188 offset:5120
	ds_read_b128 v[214:217], v188 offset:6144
	ds_read_b128 v[218:221], v188 offset:7168
	global_load_lds_dwordx4 v[222:223], off
	v_lshl_add_u64 v[222:223], v[144:145], 0, s[46:47]
	s_add_i32 m0, s55, 0xe000
	s_nop 0
	global_load_lds_dwordx4 v[222:223], off
	s_waitcnt vmcnt(8)
	s_waitcnt lgkmcnt(0)
	s_barrier
	s_setprio 1
	s_waitcnt lgkmcnt(0)
	v_mfma_f32_16x16x32_bf16 v[126:129], v[130:133], v[190:193], v[126:129]
	v_mfma_f32_16x16x32_bf16 v[122:125], v[146:149], v[190:193], v[122:125]
	v_mfma_f32_16x16x32_bf16 v[114:117], v[130:133], v[198:201], v[114:117]
	v_mfma_f32_16x16x32_bf16 v[106:109], v[146:149], v[198:201], v[106:109]
	v_mfma_f32_16x16x32_bf16 v[98:101], v[130:133], v[206:209], v[98:101]
	v_mfma_f32_16x16x32_bf16 v[90:93], v[146:149], v[206:209], v[90:93]
	v_mfma_f32_16x16x32_bf16 v[82:85], v[130:133], v[214:217], v[82:85]
	v_mfma_f32_16x16x32_bf16 v[74:77], v[146:149], v[214:217], v[74:77]
	v_mfma_f32_16x16x32_bf16 v[126:129], v[134:137], v[194:197], v[126:129]
	v_mfma_f32_16x16x32_bf16 v[122:125], v[150:153], v[194:197], v[122:125]
	v_mfma_f32_16x16x32_bf16 v[114:117], v[134:137], v[202:205], v[114:117]
	v_mfma_f32_16x16x32_bf16 v[106:109], v[150:153], v[202:205], v[106:109]
	v_mfma_f32_16x16x32_bf16 v[98:101], v[134:137], v[210:213], v[98:101]
	v_mfma_f32_16x16x32_bf16 v[90:93], v[150:153], v[210:213], v[90:93]
	v_mfma_f32_16x16x32_bf16 v[82:85], v[134:137], v[218:221], v[82:85]
	v_mfma_f32_16x16x32_bf16 v[74:77], v[150:153], v[218:221], v[74:77]
	s_setprio 0
	s_setprio 1
	v_mfma_f32_16x16x32_bf16 v[118:121], v[154:157], v[190:193], v[118:121]
	v_mfma_f32_16x16x32_bf16 v[110:113], v[178:181], v[190:193], v[110:113]
	v_mfma_f32_16x16x32_bf16 v[102:105], v[154:157], v[198:201], v[102:105]
	v_mfma_f32_16x16x32_bf16 v[94:97], v[178:181], v[198:201], v[94:97]
	v_mfma_f32_16x16x32_bf16 v[86:89], v[154:157], v[206:209], v[86:89]
	v_mfma_f32_16x16x32_bf16 v[78:81], v[178:181], v[206:209], v[78:81]
	v_mfma_f32_16x16x32_bf16 v[70:73], v[154:157], v[214:217], v[70:73]
	v_mfma_f32_16x16x32_bf16 v[66:69], v[178:181], v[214:217], v[66:69]
	v_mfma_f32_16x16x32_bf16 v[118:121], v[174:177], v[194:197], v[118:121]
	v_mfma_f32_16x16x32_bf16 v[110:113], v[182:185], v[194:197], v[110:113]
	v_mfma_f32_16x16x32_bf16 v[102:105], v[174:177], v[202:205], v[102:105]
	v_mfma_f32_16x16x32_bf16 v[94:97], v[182:185], v[202:205], v[94:97]
	v_mfma_f32_16x16x32_bf16 v[86:89], v[174:177], v[210:213], v[86:89]
	v_mfma_f32_16x16x32_bf16 v[78:81], v[182:185], v[210:213], v[78:81]
	s_setprio 3
	s_barrier
	v_mfma_f32_16x16x32_bf16 v[70:73], v[174:177], v[218:221], v[70:73]
	v_mfma_f32_16x16x32_bf16 v[66:69], v[182:185], v[218:221], v[66:69]
	s_setprio 0
	s_add_i32 s71, s64, s54
	v_lshl_add_u64 v[222:223], s[48:49], 0, v[160:161]
	s_mov_b32 m0, s71
	ds_read_b128 v[190:193], v188 offset:16384
	ds_read_b128 v[194:197], v188 offset:17408
	ds_read_b128 v[198:201], v188 offset:18432
	ds_read_b128 v[202:205], v188 offset:19456
	ds_read_b128 v[206:209], v188 offset:20480
	ds_read_b128 v[210:213], v188 offset:21504
	ds_read_b128 v[214:217], v188 offset:22528
	ds_read_b128 v[218:221], v188 offset:23552
	global_load_lds_dwordx4 v[222:223], off
	s_add_i32 m0, s71, 0x2000
	s_add_u32 s72, s48, 0x100000
	v_lshl_add_u64 v[224:225], s[48:49], 0, v[164:165]
	s_addc_u32 s73, s49, 0
	s_add_i32 s71, s65, s54
	global_load_lds_dwordx4 v[224:225], off
	v_lshl_add_u64 v[226:227], s[72:73], 0, v[160:161]
	s_mov_b32 m0, s71
	v_lshl_add_u64 v[228:229], s[50:51], 0, v[162:163]
	global_load_lds_dwordx4 v[226:227], off
	v_lshl_add_u64 v[226:227], s[72:73], 0, v[164:165]
	s_add_i32 m0, s71, 0x2000
	s_nop 0
	global_load_lds_dwordx4 v[226:227], off
	v_lshl_add_u64 v[226:227], s[50:51], 0, v[158:159]
	s_mov_b32 m0, s55
	s_nop 0
	global_load_lds_dwordx4 v[226:227], off
	s_mov_b32 m0, s56
	s_nop 0
	global_load_lds_dwordx4 v[228:229], off
	s_waitcnt vmcnt(8)
	s_waitcnt lgkmcnt(0)
	s_barrier
	s_setprio 1
	s_waitcnt lgkmcnt(0)
	v_mfma_f32_16x16x32_bf16 v[62:65], v[130:133], v[190:193], v[62:65]
	v_mfma_f32_16x16x32_bf16 v[58:61], v[146:149], v[190:193], v[58:61]
	v_mfma_f32_16x16x32_bf16 v[50:53], v[130:133], v[198:201], v[50:53]
	v_mfma_f32_16x16x32_bf16 v[42:45], v[146:149], v[198:201], v[42:45]
	v_mfma_f32_16x16x32_bf16 v[34:37], v[130:133], v[206:209], v[34:37]
	v_mfma_f32_16x16x32_bf16 v[26:29], v[146:149], v[206:209], v[26:29]
	v_mfma_f32_16x16x32_bf16 v[18:21], v[130:133], v[214:217], v[18:21]
	v_mfma_f32_16x16x32_bf16 v[10:13], v[146:149], v[214:217], v[10:13]
	v_mfma_f32_16x16x32_bf16 v[62:65], v[134:137], v[194:197], v[62:65]
	v_mfma_f32_16x16x32_bf16 v[58:61], v[150:153], v[194:197], v[58:61]
	v_mfma_f32_16x16x32_bf16 v[50:53], v[134:137], v[202:205], v[50:53]
	v_mfma_f32_16x16x32_bf16 v[42:45], v[150:153], v[202:205], v[42:45]
	v_mfma_f32_16x16x32_bf16 v[34:37], v[134:137], v[210:213], v[34:37]
	v_mfma_f32_16x16x32_bf16 v[26:29], v[150:153], v[210:213], v[26:29]
	v_mfma_f32_16x16x32_bf16 v[18:21], v[134:137], v[218:221], v[18:21]
	v_mfma_f32_16x16x32_bf16 v[10:13], v[150:153], v[218:221], v[10:13]
	s_setprio 0
	s_setprio 1
	v_mfma_f32_16x16x32_bf16 v[54:57], v[154:157], v[190:193], v[54:57]
	v_mfma_f32_16x16x32_bf16 v[46:49], v[178:181], v[190:193], v[46:49]
	v_mfma_f32_16x16x32_bf16 v[38:41], v[154:157], v[198:201], v[38:41]
	v_mfma_f32_16x16x32_bf16 v[30:33], v[178:181], v[198:201], v[30:33]
	v_mfma_f32_16x16x32_bf16 v[22:25], v[154:157], v[206:209], v[22:25]
	v_mfma_f32_16x16x32_bf16 v[14:17], v[178:181], v[206:209], v[14:17]
	v_mfma_f32_16x16x32_bf16 v[6:9], v[154:157], v[214:217], v[6:9]
	v_mfma_f32_16x16x32_bf16 v[2:5], v[178:181], v[214:217], v[2:5]
	v_mfma_f32_16x16x32_bf16 v[54:57], v[174:177], v[194:197], v[54:57]
	v_mfma_f32_16x16x32_bf16 v[46:49], v[182:185], v[194:197], v[46:49]
	s_setprio 3
	s_barrier
	v_mfma_f32_16x16x32_bf16 v[38:41], v[174:177], v[202:205], v[38:41]
	v_mfma_f32_16x16x32_bf16 v[30:33], v[182:185], v[202:205], v[30:33]
	v_mfma_f32_16x16x32_bf16 v[22:25], v[174:177], v[210:213], v[22:25]
	v_mfma_f32_16x16x32_bf16 v[14:17], v[182:185], v[210:213], v[14:17]
	v_mfma_f32_16x16x32_bf16 v[6:9], v[174:177], v[218:221], v[6:9]
	v_mfma_f32_16x16x32_bf16 v[2:5], v[182:185], v[218:221], v[2:5]
	s_setprio 0
	s_add_i32 s71, 0, 0x18000
	v_add_u32_e32 v139, s71, v186
	s_add_i32 s72, 0, 0x1c000
	ds_read_b128 v[130:133], v139
	ds_read_b128 v[134:137], v139 offset:1024
	ds_read_b128 v[146:149], v139 offset:2048
	ds_read_b128 v[150:153], v139 offset:3072
	v_add_u32_e32 v139, s72, v186
	ds_read_b128 v[154:157], v139
	ds_read_b128 v[174:177], v139 offset:1024
	ds_read_b128 v[178:181], v139 offset:2048
	ds_read_b128 v[182:185], v139 offset:3072
	s_add_u32 s50, s50, 0x100000
	s_addc_u32 s51, s51, 0
	s_mov_b32 m0, s57
	v_lshl_add_u64 v[230:231], s[50:51], 0, v[158:159]
	ds_read_b128 v[190:193], v188 offset:32768
	ds_read_b128 v[194:197], v188 offset:33792
	ds_read_b128 v[198:201], v188 offset:34816
	ds_read_b128 v[202:205], v188 offset:35840
	ds_read_b128 v[206:209], v188 offset:36864
	ds_read_b128 v[210:213], v188 offset:37888
	ds_read_b128 v[214:217], v188 offset:38912
	ds_read_b128 v[218:221], v188 offset:39936
	global_load_lds_dwordx4 v[230:231], off
	v_lshl_add_u64 v[230:231], s[50:51], 0, v[162:163]
	s_mov_b32 m0, s58
	s_nop 0
	global_load_lds_dwordx4 v[230:231], off
	s_waitcnt vmcnt(8)
	s_waitcnt lgkmcnt(0)
	s_barrier
	s_setprio 1
	s_waitcnt lgkmcnt(0)
	v_mfma_f32_16x16x32_bf16 v[126:129], v[130:133], v[190:193], v[126:129]
	v_mfma_f32_16x16x32_bf16 v[122:125], v[146:149], v[190:193], v[122:125]
	v_mfma_f32_16x16x32_bf16 v[114:117], v[130:133], v[198:201], v[114:117]
	v_mfma_f32_16x16x32_bf16 v[106:109], v[146:149], v[198:201], v[106:109]
	v_mfma_f32_16x16x32_bf16 v[98:101], v[130:133], v[206:209], v[98:101]
	v_mfma_f32_16x16x32_bf16 v[90:93], v[146:149], v[206:209], v[90:93]
	v_mfma_f32_16x16x32_bf16 v[82:85], v[130:133], v[214:217], v[82:85]
	v_mfma_f32_16x16x32_bf16 v[74:77], v[146:149], v[214:217], v[74:77]
	v_mfma_f32_16x16x32_bf16 v[126:129], v[134:137], v[194:197], v[126:129]
	v_mfma_f32_16x16x32_bf16 v[122:125], v[150:153], v[194:197], v[122:125]
	v_mfma_f32_16x16x32_bf16 v[114:117], v[134:137], v[202:205], v[114:117]
	v_mfma_f32_16x16x32_bf16 v[106:109], v[150:153], v[202:205], v[106:109]
	v_mfma_f32_16x16x32_bf16 v[98:101], v[134:137], v[210:213], v[98:101]
	v_mfma_f32_16x16x32_bf16 v[90:93], v[150:153], v[210:213], v[90:93]
	v_mfma_f32_16x16x32_bf16 v[82:85], v[134:137], v[218:221], v[82:85]
	v_mfma_f32_16x16x32_bf16 v[74:77], v[150:153], v[218:221], v[74:77]
	s_setprio 0
	s_setprio 1
	v_mfma_f32_16x16x32_bf16 v[118:121], v[154:157], v[190:193], v[118:121]
	v_mfma_f32_16x16x32_bf16 v[110:113], v[178:181], v[190:193], v[110:113]
	v_mfma_f32_16x16x32_bf16 v[102:105], v[154:157], v[198:201], v[102:105]
	v_mfma_f32_16x16x32_bf16 v[94:97], v[178:181], v[198:201], v[94:97]
	v_mfma_f32_16x16x32_bf16 v[86:89], v[154:157], v[206:209], v[86:89]
	v_mfma_f32_16x16x32_bf16 v[78:81], v[178:181], v[206:209], v[78:81]
	v_mfma_f32_16x16x32_bf16 v[70:73], v[154:157], v[214:217], v[70:73]
	v_mfma_f32_16x16x32_bf16 v[66:69], v[178:181], v[214:217], v[66:69]
	v_mfma_f32_16x16x32_bf16 v[118:121], v[174:177], v[194:197], v[118:121]
	v_mfma_f32_16x16x32_bf16 v[110:113], v[182:185], v[194:197], v[110:113]
	v_mfma_f32_16x16x32_bf16 v[102:105], v[174:177], v[202:205], v[102:105]
	v_mfma_f32_16x16x32_bf16 v[94:97], v[182:185], v[202:205], v[94:97]
	v_mfma_f32_16x16x32_bf16 v[86:89], v[174:177], v[210:213], v[86:89]
	v_mfma_f32_16x16x32_bf16 v[78:81], v[182:185], v[210:213], v[78:81]
	s_setprio 3
	s_barrier
	v_mfma_f32_16x16x32_bf16 v[70:73], v[174:177], v[218:221], v[70:73]
	v_mfma_f32_16x16x32_bf16 v[66:69], v[182:185], v[218:221], v[66:69]
	s_setprio 0
	s_add_i32 s50, s71, s54
	v_lshl_add_u64 v[222:223], v[222:223], 0, s[30:31]
	s_mov_b32 m0, s50
	ds_read_b128 v[190:193], v188 offset:49152
	ds_read_b128 v[194:197], v188 offset:50176
	ds_read_b128 v[198:201], v188 offset:51200
	ds_read_b128 v[202:205], v188 offset:52224
	ds_read_b128 v[206:209], v188 offset:53248
	ds_read_b128 v[210:213], v188 offset:54272
	ds_read_b128 v[214:217], v188 offset:55296
	ds_read_b128 v[218:221], v188 offset:56320
	global_load_lds_dwordx4 v[222:223], off
	s_add_i32 m0, s50, 0x2000
	s_add_u32 s48, s48, 0x100080
	v_lshl_add_u64 v[222:223], v[224:225], 0, s[30:31]
	s_addc_u32 s49, s49, 0
	s_add_i32 s50, s72, s54
	global_load_lds_dwordx4 v[222:223], off
	v_lshl_add_u64 v[222:223], s[48:49], 0, v[160:161]
	s_mov_b32 m0, s50
	s_nop 0
	global_load_lds_dwordx4 v[222:223], off
	v_lshl_add_u64 v[222:223], s[48:49], 0, v[164:165]
	s_add_i32 m0, s50, 0x2000
	s_nop 0
	global_load_lds_dwordx4 v[222:223], off
	v_lshl_add_u64 v[222:223], v[226:227], 0, s[30:31]
	s_mov_b32 m0, s60
	s_nop 0
	global_load_lds_dwordx4 v[222:223], off
	v_lshl_add_u64 v[222:223], v[228:229], 0, s[30:31]
	s_mov_b32 m0, s61
	s_nop 0
	global_load_lds_dwordx4 v[222:223], off
	s_waitcnt vmcnt(8)
	s_waitcnt lgkmcnt(0)
	s_barrier
	s_setprio 1
	s_waitcnt lgkmcnt(0)
	v_mfma_f32_16x16x32_bf16 v[62:65], v[130:133], v[190:193], v[62:65]
	v_mfma_f32_16x16x32_bf16 v[58:61], v[146:149], v[190:193], v[58:61]
	v_mfma_f32_16x16x32_bf16 v[50:53], v[130:133], v[198:201], v[50:53]
	v_mfma_f32_16x16x32_bf16 v[42:45], v[146:149], v[198:201], v[42:45]
	v_mfma_f32_16x16x32_bf16 v[34:37], v[130:133], v[206:209], v[34:37]
	v_mfma_f32_16x16x32_bf16 v[26:29], v[146:149], v[206:209], v[26:29]
	v_mfma_f32_16x16x32_bf16 v[18:21], v[130:133], v[214:217], v[18:21]
	v_mfma_f32_16x16x32_bf16 v[10:13], v[146:149], v[214:217], v[10:13]
	v_mfma_f32_16x16x32_bf16 v[62:65], v[134:137], v[194:197], v[62:65]
	v_mfma_f32_16x16x32_bf16 v[58:61], v[150:153], v[194:197], v[58:61]
	v_mfma_f32_16x16x32_bf16 v[50:53], v[134:137], v[202:205], v[50:53]
	v_mfma_f32_16x16x32_bf16 v[42:45], v[150:153], v[202:205], v[42:45]
	v_mfma_f32_16x16x32_bf16 v[34:37], v[134:137], v[210:213], v[34:37]
	v_mfma_f32_16x16x32_bf16 v[26:29], v[150:153], v[210:213], v[26:29]
	v_mfma_f32_16x16x32_bf16 v[18:21], v[134:137], v[218:221], v[18:21]
	v_mfma_f32_16x16x32_bf16 v[10:13], v[150:153], v[218:221], v[10:13]
	s_setprio 0
	s_setprio 1
	v_mfma_f32_16x16x32_bf16 v[54:57], v[154:157], v[190:193], v[54:57]
	v_mfma_f32_16x16x32_bf16 v[46:49], v[178:181], v[190:193], v[46:49]
	v_mfma_f32_16x16x32_bf16 v[38:41], v[154:157], v[198:201], v[38:41]
	v_mfma_f32_16x16x32_bf16 v[30:33], v[178:181], v[198:201], v[30:33]
	v_mfma_f32_16x16x32_bf16 v[22:25], v[154:157], v[206:209], v[22:25]
	v_mfma_f32_16x16x32_bf16 v[14:17], v[178:181], v[206:209], v[14:17]
	v_mfma_f32_16x16x32_bf16 v[6:9], v[154:157], v[214:217], v[6:9]
	v_mfma_f32_16x16x32_bf16 v[2:5], v[178:181], v[214:217], v[2:5]
	v_mfma_f32_16x16x32_bf16 v[54:57], v[174:177], v[194:197], v[54:57]
	v_mfma_f32_16x16x32_bf16 v[46:49], v[182:185], v[194:197], v[46:49]
	s_setprio 3
	s_barrier
	v_mfma_f32_16x16x32_bf16 v[38:41], v[174:177], v[202:205], v[38:41]
	v_mfma_f32_16x16x32_bf16 v[30:33], v[182:185], v[202:205], v[30:33]
	v_mfma_f32_16x16x32_bf16 v[22:25], v[174:177], v[210:213], v[22:25]
	v_mfma_f32_16x16x32_bf16 v[14:17], v[182:185], v[210:213], v[14:17]
	v_mfma_f32_16x16x32_bf16 v[6:9], v[174:177], v[218:221], v[6:9]
	v_mfma_f32_16x16x32_bf16 v[2:5], v[182:185], v[218:221], v[2:5]
	s_setprio 0
	s_add_i32 s70, s70, 2
	s_add_u32 s46, s46, 0x100
	s_addc_u32 s47, s47, 0
	s_cmp_gt_u32 s70, 61
	s_cbranch_scc1 .LBB0_543

.LBB0_618:
	ds_read_b128 v[146:149], v154
	ds_read_b128 v[158:161], v154 offset:1024
	ds_read_b128 v[162:165], v154 offset:2048
	ds_read_b128 v[166:169], v154 offset:3072
	ds_read_b128 v[170:173], v155
	ds_read_b128 v[174:177], v155 offset:1024
	ds_read_b128 v[178:181], v155 offset:2048
	ds_read_b128 v[182:185], v155 offset:3072
	s_add_u32 s48, s46, 0xfff00080
	s_addc_u32 s49, s47, -1
	s_cmp_eq_u32 s68, 60
	s_cselect_b32 s51, s39, s49
	s_cselect_b32 s50, s64, s48
	s_cselect_b32 s49, s37, s67
	s_cselect_b32 s48, s65, s66
	v_lshl_add_u64 v[150:151], s[46:47], 0, v[138:139]
	s_add_i32 m0, s45, 0xc000
	ds_read_b128 v[186:189], v156
	ds_read_b128 v[190:193], v156 offset:1024
	ds_read_b128 v[194:197], v156 offset:2048
	ds_read_b128 v[198:201], v156 offset:3072
	ds_read_b128 v[202:205], v156 offset:4096
	ds_read_b128 v[206:209], v156 offset:5120
	ds_read_b128 v[210:213], v156 offset:6144
	ds_read_b128 v[214:217], v156 offset:7168
	global_load_lds_dwordx4 v[150:151], off
	v_lshl_add_u64 v[150:151], s[46:47], 0, v[140:141]
	s_add_i32 m0, s45, 0xe000
	s_nop 0
	global_load_lds_dwordx4 v[150:151], off
	s_waitcnt vmcnt(8)
	s_waitcnt lgkmcnt(0)
	s_barrier
	s_setprio 1
	s_waitcnt lgkmcnt(0)
	v_mfma_f32_16x16x32_bf16 v[126:129], v[146:149], v[186:189], v[126:129]
	v_mfma_f32_16x16x32_bf16 v[122:125], v[162:165], v[186:189], v[122:125]
	v_mfma_f32_16x16x32_bf16 v[118:121], v[146:149], v[194:197], v[118:121]
	v_mfma_f32_16x16x32_bf16 v[114:117], v[162:165], v[194:197], v[114:117]
	v_mfma_f32_16x16x32_bf16 v[102:105], v[146:149], v[202:205], v[102:105]
	v_mfma_f32_16x16x32_bf16 v[98:101], v[162:165], v[202:205], v[98:101]
	v_mfma_f32_16x16x32_bf16 v[86:89], v[146:149], v[210:213], v[86:89]
	v_mfma_f32_16x16x32_bf16 v[78:81], v[162:165], v[210:213], v[78:81]
	v_mfma_f32_16x16x32_bf16 v[126:129], v[158:161], v[190:193], v[126:129]
	v_mfma_f32_16x16x32_bf16 v[122:125], v[166:169], v[190:193], v[122:125]
	v_mfma_f32_16x16x32_bf16 v[118:121], v[158:161], v[198:201], v[118:121]
	v_mfma_f32_16x16x32_bf16 v[114:117], v[166:169], v[198:201], v[114:117]
	v_mfma_f32_16x16x32_bf16 v[102:105], v[158:161], v[206:209], v[102:105]
	v_mfma_f32_16x16x32_bf16 v[98:101], v[166:169], v[206:209], v[98:101]
	v_mfma_f32_16x16x32_bf16 v[86:89], v[158:161], v[214:217], v[86:89]
	v_mfma_f32_16x16x32_bf16 v[78:81], v[166:169], v[214:217], v[78:81]
	s_setprio 0
	s_setprio 1
	v_mfma_f32_16x16x32_bf16 v[110:113], v[170:173], v[186:189], v[110:113]
	v_mfma_f32_16x16x32_bf16 v[106:109], v[178:181], v[186:189], v[106:109]
	v_mfma_f32_16x16x32_bf16 v[94:97], v[170:173], v[194:197], v[94:97]
	v_mfma_f32_16x16x32_bf16 v[90:93], v[178:181], v[194:197], v[90:93]
	v_mfma_f32_16x16x32_bf16 v[82:85], v[170:173], v[202:205], v[82:85]
	v_mfma_f32_16x16x32_bf16 v[74:77], v[178:181], v[202:205], v[74:77]
	v_mfma_f32_16x16x32_bf16 v[70:73], v[170:173], v[210:213], v[70:73]
	v_mfma_f32_16x16x32_bf16 v[66:69], v[178:181], v[210:213], v[66:69]
	v_mfma_f32_16x16x32_bf16 v[110:113], v[174:177], v[190:193], v[110:113]
	v_mfma_f32_16x16x32_bf16 v[106:109], v[182:185], v[190:193], v[106:109]
	v_mfma_f32_16x16x32_bf16 v[94:97], v[174:177], v[198:201], v[94:97]
	v_mfma_f32_16x16x32_bf16 v[90:93], v[182:185], v[198:201], v[90:93]
	v_mfma_f32_16x16x32_bf16 v[82:85], v[174:177], v[206:209], v[82:85]
	v_mfma_f32_16x16x32_bf16 v[74:77], v[182:185], v[206:209], v[74:77]
	s_setprio 3
	s_barrier
	v_mfma_f32_16x16x32_bf16 v[70:73], v[174:177], v[214:217], v[70:73]
	v_mfma_f32_16x16x32_bf16 v[66:69], v[182:185], v[214:217], v[66:69]
	s_setprio 0
	s_add_i32 s69, s61, s53
	v_lshl_add_u64 v[150:151], s[48:49], 0, v[132:133]
	s_mov_b32 m0, s69
	ds_read_b128 v[186:189], v156 offset:16384
	ds_read_b128 v[190:193], v156 offset:17408
	ds_read_b128 v[194:197], v156 offset:18432
	ds_read_b128 v[198:201], v156 offset:19456
	ds_read_b128 v[202:205], v156 offset:20480
	ds_read_b128 v[206:209], v156 offset:21504
	ds_read_b128 v[210:213], v156 offset:22528
	ds_read_b128 v[214:217], v156 offset:23552
	global_load_lds_dwordx4 v[150:151], off
	s_add_i32 m0, s69, 0x2000
	s_add_u32 s70, s48, 0x100000
	v_lshl_add_u64 v[218:219], s[48:49], 0, v[136:137]
	s_addc_u32 s71, s49, 0
	s_add_i32 s69, s62, s53
	global_load_lds_dwordx4 v[218:219], off
	v_lshl_add_u64 v[220:221], s[70:71], 0, v[132:133]
	s_mov_b32 m0, s69
	v_lshl_add_u64 v[222:223], s[50:51], 0, v[134:135]
	global_load_lds_dwordx4 v[220:221], off
	v_lshl_add_u64 v[220:221], s[70:71], 0, v[136:137]
	s_add_i32 m0, s69, 0x2000
	s_nop 0
	global_load_lds_dwordx4 v[220:221], off
	v_lshl_add_u64 v[220:221], s[50:51], 0, v[130:131]
	s_mov_b32 m0, s45
	s_nop 0
	global_load_lds_dwordx4 v[220:221], off
	s_mov_b32 m0, s54
	s_nop 0
	global_load_lds_dwordx4 v[222:223], off
	s_waitcnt vmcnt(8)
	s_waitcnt lgkmcnt(0)
	s_barrier
	s_setprio 1
	s_waitcnt lgkmcnt(0)
	v_mfma_f32_16x16x32_bf16 v[62:65], v[146:149], v[186:189], v[62:65]
	v_mfma_f32_16x16x32_bf16 v[58:61], v[162:165], v[186:189], v[58:61]
	v_mfma_f32_16x16x32_bf16 v[50:53], v[146:149], v[194:197], v[50:53]
	v_mfma_f32_16x16x32_bf16 v[42:45], v[162:165], v[194:197], v[42:45]
	v_mfma_f32_16x16x32_bf16 v[38:41], v[146:149], v[202:205], v[38:41]
	v_mfma_f32_16x16x32_bf16 v[30:33], v[162:165], v[202:205], v[30:33]
	v_mfma_f32_16x16x32_bf16 v[22:25], v[146:149], v[210:213], v[22:25]
	v_mfma_f32_16x16x32_bf16 v[14:17], v[162:165], v[210:213], v[14:17]
	v_mfma_f32_16x16x32_bf16 v[62:65], v[158:161], v[190:193], v[62:65]
	v_mfma_f32_16x16x32_bf16 v[58:61], v[166:169], v[190:193], v[58:61]
	v_mfma_f32_16x16x32_bf16 v[50:53], v[158:161], v[198:201], v[50:53]
	v_mfma_f32_16x16x32_bf16 v[42:45], v[166:169], v[198:201], v[42:45]
	v_mfma_f32_16x16x32_bf16 v[38:41], v[158:161], v[206:209], v[38:41]
	v_mfma_f32_16x16x32_bf16 v[30:33], v[166:169], v[206:209], v[30:33]
	v_mfma_f32_16x16x32_bf16 v[22:25], v[158:161], v[214:217], v[22:25]
	v_mfma_f32_16x16x32_bf16 v[14:17], v[166:169], v[214:217], v[14:17]
	s_setprio 0
	s_setprio 1
	v_mfma_f32_16x16x32_bf16 v[54:57], v[170:173], v[186:189], v[54:57]
	v_mfma_f32_16x16x32_bf16 v[46:49], v[178:181], v[186:189], v[46:49]
	v_mfma_f32_16x16x32_bf16 v[34:37], v[170:173], v[194:197], v[34:37]
	v_mfma_f32_16x16x32_bf16 v[26:29], v[178:181], v[194:197], v[26:29]
	v_mfma_f32_16x16x32_bf16 v[18:21], v[170:173], v[202:205], v[18:21]
	v_mfma_f32_16x16x32_bf16 v[10:13], v[178:181], v[202:205], v[10:13]
	v_mfma_f32_16x16x32_bf16 v[6:9], v[170:173], v[210:213], v[6:9]
	v_mfma_f32_16x16x32_bf16 v[2:5], v[178:181], v[210:213], v[2:5]
	v_mfma_f32_16x16x32_bf16 v[54:57], v[174:177], v[190:193], v[54:57]
	v_mfma_f32_16x16x32_bf16 v[46:49], v[182:185], v[190:193], v[46:49]
	s_setprio 3
	s_barrier
	v_mfma_f32_16x16x32_bf16 v[34:37], v[174:177], v[198:201], v[34:37]
	v_mfma_f32_16x16x32_bf16 v[26:29], v[182:185], v[198:201], v[26:29]
	v_mfma_f32_16x16x32_bf16 v[18:21], v[174:177], v[206:209], v[18:21]
	v_mfma_f32_16x16x32_bf16 v[10:13], v[182:185], v[206:209], v[10:13]
	v_mfma_f32_16x16x32_bf16 v[6:9], v[174:177], v[214:217], v[6:9]
	v_mfma_f32_16x16x32_bf16 v[2:5], v[182:185], v[214:217], v[2:5]
	s_setprio 0
	s_add_i32 s69, 0, 0x18000
	v_add_u32_e32 v157, s69, v152
	s_add_i32 s70, 0, 0x1c000
	ds_read_b128 v[146:149], v157
	ds_read_b128 v[158:161], v157 offset:1024
	ds_read_b128 v[162:165], v157 offset:2048
	ds_read_b128 v[166:169], v157 offset:3072
	v_add_u32_e32 v157, s70, v152
	ds_read_b128 v[170:173], v157
	ds_read_b128 v[174:177], v157 offset:1024
	ds_read_b128 v[178:181], v157 offset:2048
	ds_read_b128 v[182:185], v157 offset:3072
	s_add_u32 s50, s50, 0x100000
	s_addc_u32 s51, s51, 0
	s_mov_b32 m0, s55
	v_lshl_add_u64 v[224:225], s[50:51], 0, v[130:131]
	ds_read_b128 v[186:189], v156 offset:32768
	ds_read_b128 v[190:193], v156 offset:33792
	ds_read_b128 v[194:197], v156 offset:34816
	ds_read_b128 v[198:201], v156 offset:35840
	ds_read_b128 v[202:205], v156 offset:36864
	ds_read_b128 v[206:209], v156 offset:37888
	ds_read_b128 v[210:213], v156 offset:38912
	ds_read_b128 v[214:217], v156 offset:39936
	global_load_lds_dwordx4 v[224:225], off
	v_lshl_add_u64 v[224:225], s[50:51], 0, v[134:135]
	s_mov_b32 m0, s56
	s_nop 0
	global_load_lds_dwordx4 v[224:225], off
	s_waitcnt vmcnt(8)
	s_waitcnt lgkmcnt(0)
	s_barrier
	s_setprio 1
	s_waitcnt lgkmcnt(0)
	v_mfma_f32_16x16x32_bf16 v[126:129], v[146:149], v[186:189], v[126:129]
	v_mfma_f32_16x16x32_bf16 v[122:125], v[162:165], v[186:189], v[122:125]
	v_mfma_f32_16x16x32_bf16 v[118:121], v[146:149], v[194:197], v[118:121]
	v_mfma_f32_16x16x32_bf16 v[114:117], v[162:165], v[194:197], v[114:117]
	v_mfma_f32_16x16x32_bf16 v[102:105], v[146:149], v[202:205], v[102:105]
	v_mfma_f32_16x16x32_bf16 v[98:101], v[162:165], v[202:205], v[98:101]
	v_mfma_f32_16x16x32_bf16 v[86:89], v[146:149], v[210:213], v[86:89]
	v_mfma_f32_16x16x32_bf16 v[78:81], v[162:165], v[210:213], v[78:81]
	v_mfma_f32_16x16x32_bf16 v[126:129], v[158:161], v[190:193], v[126:129]
	v_mfma_f32_16x16x32_bf16 v[122:125], v[166:169], v[190:193], v[122:125]
	v_mfma_f32_16x16x32_bf16 v[118:121], v[158:161], v[198:201], v[118:121]
	v_mfma_f32_16x16x32_bf16 v[114:117], v[166:169], v[198:201], v[114:117]
	v_mfma_f32_16x16x32_bf16 v[102:105], v[158:161], v[206:209], v[102:105]
	v_mfma_f32_16x16x32_bf16 v[98:101], v[166:169], v[206:209], v[98:101]
	v_mfma_f32_16x16x32_bf16 v[86:89], v[158:161], v[214:217], v[86:89]
	v_mfma_f32_16x16x32_bf16 v[78:81], v[166:169], v[214:217], v[78:81]
	s_setprio 0
	s_setprio 1
	v_mfma_f32_16x16x32_bf16 v[110:113], v[170:173], v[186:189], v[110:113]
	v_mfma_f32_16x16x32_bf16 v[106:109], v[178:181], v[186:189], v[106:109]
	v_mfma_f32_16x16x32_bf16 v[94:97], v[170:173], v[194:197], v[94:97]
	v_mfma_f32_16x16x32_bf16 v[90:93], v[178:181], v[194:197], v[90:93]
	v_mfma_f32_16x16x32_bf16 v[82:85], v[170:173], v[202:205], v[82:85]
	v_mfma_f32_16x16x32_bf16 v[74:77], v[178:181], v[202:205], v[74:77]
	v_mfma_f32_16x16x32_bf16 v[70:73], v[170:173], v[210:213], v[70:73]
	v_mfma_f32_16x16x32_bf16 v[66:69], v[178:181], v[210:213], v[66:69]
	v_mfma_f32_16x16x32_bf16 v[110:113], v[174:177], v[190:193], v[110:113]
	v_mfma_f32_16x16x32_bf16 v[106:109], v[182:185], v[190:193], v[106:109]
	v_mfma_f32_16x16x32_bf16 v[94:97], v[174:177], v[198:201], v[94:97]
	v_mfma_f32_16x16x32_bf16 v[90:93], v[182:185], v[198:201], v[90:93]
	v_mfma_f32_16x16x32_bf16 v[82:85], v[174:177], v[206:209], v[82:85]
	v_mfma_f32_16x16x32_bf16 v[74:77], v[182:185], v[206:209], v[74:77]
	s_setprio 3
	s_barrier
	v_mfma_f32_16x16x32_bf16 v[70:73], v[174:177], v[214:217], v[70:73]
	v_mfma_f32_16x16x32_bf16 v[66:69], v[182:185], v[214:217], v[66:69]
	s_setprio 0
	s_add_i32 s50, s69, s53
	v_lshl_add_u64 v[150:151], v[150:151], 0, s[28:29]
	s_mov_b32 m0, s50
	ds_read_b128 v[186:189], v156 offset:49152
	ds_read_b128 v[190:193], v156 offset:50176
	ds_read_b128 v[194:197], v156 offset:51200
	ds_read_b128 v[198:201], v156 offset:52224
	ds_read_b128 v[202:205], v156 offset:53248
	ds_read_b128 v[206:209], v156 offset:54272
	ds_read_b128 v[210:213], v156 offset:55296
	ds_read_b128 v[214:217], v156 offset:56320
	global_load_lds_dwordx4 v[150:151], off
	s_add_i32 m0, s50, 0x2000
	s_add_u32 s48, s48, 0x100080
	v_lshl_add_u64 v[150:151], v[218:219], 0, s[28:29]
	s_addc_u32 s49, s49, 0
	s_add_i32 s50, s70, s53
	global_load_lds_dwordx4 v[150:151], off
	v_lshl_add_u64 v[150:151], s[48:49], 0, v[132:133]
	s_mov_b32 m0, s50
	s_nop 0
	global_load_lds_dwordx4 v[150:151], off
	v_lshl_add_u64 v[150:151], s[48:49], 0, v[136:137]
	s_add_i32 m0, s50, 0x2000
	s_nop 0
	global_load_lds_dwordx4 v[150:151], off
	v_lshl_add_u64 v[150:151], v[220:221], 0, s[28:29]
	s_mov_b32 m0, s58
	s_nop 0
	global_load_lds_dwordx4 v[150:151], off
	v_lshl_add_u64 v[150:151], v[222:223], 0, s[28:29]
	s_mov_b32 m0, s59
	s_nop 0
	global_load_lds_dwordx4 v[150:151], off
	s_waitcnt vmcnt(8)
	s_waitcnt lgkmcnt(0)
	s_barrier
	s_setprio 1
	s_waitcnt lgkmcnt(0)
	v_mfma_f32_16x16x32_bf16 v[62:65], v[146:149], v[186:189], v[62:65]
	v_mfma_f32_16x16x32_bf16 v[58:61], v[162:165], v[186:189], v[58:61]
	v_mfma_f32_16x16x32_bf16 v[50:53], v[146:149], v[194:197], v[50:53]
	v_mfma_f32_16x16x32_bf16 v[42:45], v[162:165], v[194:197], v[42:45]
	v_mfma_f32_16x16x32_bf16 v[38:41], v[146:149], v[202:205], v[38:41]
	v_mfma_f32_16x16x32_bf16 v[30:33], v[162:165], v[202:205], v[30:33]
	v_mfma_f32_16x16x32_bf16 v[22:25], v[146:149], v[210:213], v[22:25]
	v_mfma_f32_16x16x32_bf16 v[14:17], v[162:165], v[210:213], v[14:17]
	v_mfma_f32_16x16x32_bf16 v[62:65], v[158:161], v[190:193], v[62:65]
	v_mfma_f32_16x16x32_bf16 v[58:61], v[166:169], v[190:193], v[58:61]
	v_mfma_f32_16x16x32_bf16 v[50:53], v[158:161], v[198:201], v[50:53]
	v_mfma_f32_16x16x32_bf16 v[42:45], v[166:169], v[198:201], v[42:45]
	v_mfma_f32_16x16x32_bf16 v[38:41], v[158:161], v[206:209], v[38:41]
	v_mfma_f32_16x16x32_bf16 v[30:33], v[166:169], v[206:209], v[30:33]
	v_mfma_f32_16x16x32_bf16 v[22:25], v[158:161], v[214:217], v[22:25]
	v_mfma_f32_16x16x32_bf16 v[14:17], v[166:169], v[214:217], v[14:17]
	s_setprio 0
	s_setprio 1
	v_mfma_f32_16x16x32_bf16 v[54:57], v[170:173], v[186:189], v[54:57]
	v_mfma_f32_16x16x32_bf16 v[46:49], v[178:181], v[186:189], v[46:49]
	v_mfma_f32_16x16x32_bf16 v[34:37], v[170:173], v[194:197], v[34:37]
	v_mfma_f32_16x16x32_bf16 v[26:29], v[178:181], v[194:197], v[26:29]
	v_mfma_f32_16x16x32_bf16 v[18:21], v[170:173], v[202:205], v[18:21]
	v_mfma_f32_16x16x32_bf16 v[10:13], v[178:181], v[202:205], v[10:13]
	v_mfma_f32_16x16x32_bf16 v[6:9], v[170:173], v[210:213], v[6:9]
	v_mfma_f32_16x16x32_bf16 v[2:5], v[178:181], v[210:213], v[2:5]
	v_mfma_f32_16x16x32_bf16 v[54:57], v[174:177], v[190:193], v[54:57]
	v_mfma_f32_16x16x32_bf16 v[46:49], v[182:185], v[190:193], v[46:49]
	s_setprio 3
	s_barrier
	v_mfma_f32_16x16x32_bf16 v[34:37], v[174:177], v[198:201], v[34:37]
	v_mfma_f32_16x16x32_bf16 v[26:29], v[182:185], v[198:201], v[26:29]
	v_mfma_f32_16x16x32_bf16 v[18:21], v[174:177], v[206:209], v[18:21]
	v_mfma_f32_16x16x32_bf16 v[10:13], v[182:185], v[206:209], v[10:13]
	v_mfma_f32_16x16x32_bf16 v[6:9], v[174:177], v[214:217], v[6:9]
	v_mfma_f32_16x16x32_bf16 v[2:5], v[182:185], v[214:217], v[2:5]
	s_setprio 0
	s_add_i32 s68, s68, 2
	s_add_u32 s46, s46, 0x100
	s_addc_u32 s47, s47, 0
	s_add_u32 s66, s66, 0x100
	s_addc_u32 s67, s67, 0
	s_cmp_gt_u32 s68, 61
	s_cbranch_scc0 .LBB0_618
	s_and_b64 vcc, exec, s[30:31]
	s_cbranch_vccz .LBB0_621
	s_barrier

.LBB0_743:
	ds_read_b128 v[130:133], v197
	ds_read_b128 v[134:137], v197 offset:1024
	ds_read_b128 v[138:141], v197 offset:2048
	ds_read_b128 v[142:145], v197 offset:3072
	ds_read_b128 v[146:149], v198
	ds_read_b128 v[150:153], v198 offset:1024
	ds_read_b128 v[154:157], v198 offset:2048
	ds_read_b128 v[158:161], v198 offset:3072
	s_add_u32 s72, s70, 0xfff00080
	s_addc_u32 s73, s71, -1
	s_cmp_eq_u32 s95, 60
	s_cselect_b32 s75, s61, s73
	s_cselect_b32 s74, s67, s72
	s_cselect_b32 s73, s59, s94
	s_cselect_b32 s72, s69, s93
	v_lshl_add_u64 v[184:185], s[70:71], 0, v[176:177]
	s_add_i32 m0, s78, 0xc000
	ds_read_b128 v[200:203], v199
	ds_read_b128 v[204:207], v199 offset:1024
	ds_read_b128 v[208:211], v199 offset:2048
	ds_read_b128 v[212:215], v199 offset:3072
	ds_read_b128 v[216:219], v199 offset:4096
	ds_read_b128 v[220:223], v199 offset:5120
	ds_read_b128 v[224:227], v199 offset:6144
	ds_read_b128 v[228:231], v199 offset:7168
	global_load_lds_dwordx4 v[184:185], off
	v_lshl_add_u64 v[184:185], s[70:71], 0, v[178:179]
	s_add_i32 m0, s78, 0xe000
	s_nop 0
	global_load_lds_dwordx4 v[184:185], off
	s_waitcnt vmcnt(8)
	s_waitcnt lgkmcnt(0)
	s_barrier
	s_setprio 1
	s_waitcnt lgkmcnt(0)
	v_mfma_f32_16x16x32_bf16 v[102:105], v[130:133], v[200:203], v[102:105]
	v_mfma_f32_16x16x32_bf16 v[98:101], v[138:141], v[200:203], v[98:101]
	v_mfma_f32_16x16x32_bf16 v[110:113], v[130:133], v[208:211], v[110:113]
	v_mfma_f32_16x16x32_bf16 v[106:109], v[138:141], v[208:211], v[106:109]
	v_mfma_f32_16x16x32_bf16 v[118:121], v[130:133], v[216:219], v[118:121]
	v_mfma_f32_16x16x32_bf16 v[114:117], v[138:141], v[216:219], v[114:117]
	v_mfma_f32_16x16x32_bf16 v[126:129], v[130:133], v[224:227], v[126:129]
	v_mfma_f32_16x16x32_bf16 v[122:125], v[138:141], v[224:227], v[122:125]
	v_mfma_f32_16x16x32_bf16 v[102:105], v[134:137], v[204:207], v[102:105]
	v_mfma_f32_16x16x32_bf16 v[98:101], v[142:145], v[204:207], v[98:101]
	v_mfma_f32_16x16x32_bf16 v[110:113], v[134:137], v[212:215], v[110:113]
	v_mfma_f32_16x16x32_bf16 v[106:109], v[142:145], v[212:215], v[106:109]
	v_mfma_f32_16x16x32_bf16 v[118:121], v[134:137], v[220:223], v[118:121]
	v_mfma_f32_16x16x32_bf16 v[114:117], v[142:145], v[220:223], v[114:117]
	v_mfma_f32_16x16x32_bf16 v[126:129], v[134:137], v[228:231], v[126:129]
	v_mfma_f32_16x16x32_bf16 v[122:125], v[142:145], v[228:231], v[122:125]
	s_setprio 0
	s_setprio 1
	v_mfma_f32_16x16x32_bf16 v[38:41], v[146:149], v[200:203], v[38:41]
	v_mfma_f32_16x16x32_bf16 v[34:37], v[154:157], v[200:203], v[34:37]
	v_mfma_f32_16x16x32_bf16 v[46:49], v[146:149], v[208:211], v[46:49]
	v_mfma_f32_16x16x32_bf16 v[42:45], v[154:157], v[208:211], v[42:45]
	v_mfma_f32_16x16x32_bf16 v[54:57], v[146:149], v[216:219], v[54:57]
	v_mfma_f32_16x16x32_bf16 v[50:53], v[154:157], v[216:219], v[50:53]
	v_mfma_f32_16x16x32_bf16 v[62:65], v[146:149], v[224:227], v[62:65]
	v_mfma_f32_16x16x32_bf16 v[58:61], v[154:157], v[224:227], v[58:61]
	v_mfma_f32_16x16x32_bf16 v[38:41], v[150:153], v[204:207], v[38:41]
	v_mfma_f32_16x16x32_bf16 v[34:37], v[158:161], v[204:207], v[34:37]
	v_mfma_f32_16x16x32_bf16 v[46:49], v[150:153], v[212:215], v[46:49]
	v_mfma_f32_16x16x32_bf16 v[42:45], v[158:161], v[212:215], v[42:45]
	v_mfma_f32_16x16x32_bf16 v[54:57], v[150:153], v[220:223], v[54:57]
	v_mfma_f32_16x16x32_bf16 v[50:53], v[158:161], v[220:223], v[50:53]
	s_setprio 3
	s_barrier
	v_mfma_f32_16x16x32_bf16 v[62:65], v[150:153], v[228:231], v[62:65]
	v_mfma_f32_16x16x32_bf16 v[58:61], v[158:161], v[228:231], v[58:61]
	s_setprio 0
	s_add_i32 s96, s90, s77
	v_lshl_add_u64 v[184:185], s[72:73], 0, v[164:165]
	s_mov_b32 m0, s96
	ds_read_b128 v[200:203], v199 offset:16384
	ds_read_b128 v[204:207], v199 offset:17408
	ds_read_b128 v[208:211], v199 offset:18432
	ds_read_b128 v[212:215], v199 offset:19456
	ds_read_b128 v[216:219], v199 offset:20480
	ds_read_b128 v[220:223], v199 offset:21504
	ds_read_b128 v[224:227], v199 offset:22528
	ds_read_b128 v[228:231], v199 offset:23552
	global_load_lds_dwordx4 v[184:185], off
	s_add_i32 m0, s96, 0x2000
	s_add_u32 s96, s72, 0x100000
	v_lshl_add_u64 v[232:233], s[72:73], 0, v[168:169]
	s_addc_u32 s97, s73, 0
	s_add_i32 vcc_lo, s91, s77
	global_load_lds_dwordx4 v[232:233], off
	v_lshl_add_u64 v[234:235], s[96:97], 0, v[164:165]
	s_mov_b32 m0, vcc_lo
	v_lshl_add_u64 v[236:237], s[74:75], 0, v[166:167]
	global_load_lds_dwordx4 v[234:235], off
	v_lshl_add_u64 v[234:235], s[96:97], 0, v[168:169]
	s_add_i32 m0, vcc_lo, 0x2000
	s_nop 0
	global_load_lds_dwordx4 v[234:235], off
	v_lshl_add_u64 v[234:235], s[74:75], 0, v[162:163]
	s_mov_b32 m0, s78
	s_nop 0
	global_load_lds_dwordx4 v[234:235], off
	s_mov_b32 m0, s79
	s_nop 0
	global_load_lds_dwordx4 v[236:237], off
	s_waitcnt vmcnt(8)
	s_waitcnt lgkmcnt(0)
	s_barrier
	s_setprio 1
	s_waitcnt lgkmcnt(0)
	v_mfma_f32_16x16x32_bf16 v[70:73], v[130:133], v[200:203], v[70:73]
	v_mfma_f32_16x16x32_bf16 v[66:69], v[138:141], v[200:203], v[66:69]
	v_mfma_f32_16x16x32_bf16 v[78:81], v[130:133], v[208:211], v[78:81]
	v_mfma_f32_16x16x32_bf16 v[74:77], v[138:141], v[208:211], v[74:77]
	v_mfma_f32_16x16x32_bf16 v[86:89], v[130:133], v[216:219], v[86:89]
	v_mfma_f32_16x16x32_bf16 v[82:85], v[138:141], v[216:219], v[82:85]
	v_mfma_f32_16x16x32_bf16 v[94:97], v[130:133], v[224:227], v[94:97]
	v_mfma_f32_16x16x32_bf16 v[90:93], v[138:141], v[224:227], v[90:93]
	v_mfma_f32_16x16x32_bf16 v[70:73], v[134:137], v[204:207], v[70:73]
	v_mfma_f32_16x16x32_bf16 v[66:69], v[142:145], v[204:207], v[66:69]
	v_mfma_f32_16x16x32_bf16 v[78:81], v[134:137], v[212:215], v[78:81]
	v_mfma_f32_16x16x32_bf16 v[74:77], v[142:145], v[212:215], v[74:77]
	v_mfma_f32_16x16x32_bf16 v[86:89], v[134:137], v[220:223], v[86:89]
	v_mfma_f32_16x16x32_bf16 v[82:85], v[142:145], v[220:223], v[82:85]
	v_mfma_f32_16x16x32_bf16 v[94:97], v[134:137], v[228:231], v[94:97]
	v_mfma_f32_16x16x32_bf16 v[90:93], v[142:145], v[228:231], v[90:93]
	s_setprio 0
	s_setprio 1
	v_mfma_f32_16x16x32_bf16 v[6:9], v[146:149], v[200:203], v[6:9]
	v_mfma_f32_16x16x32_bf16 v[2:5], v[154:157], v[200:203], v[2:5]
	v_mfma_f32_16x16x32_bf16 v[14:17], v[146:149], v[208:211], v[14:17]
	v_mfma_f32_16x16x32_bf16 v[10:13], v[154:157], v[208:211], v[10:13]
	v_mfma_f32_16x16x32_bf16 v[22:25], v[146:149], v[216:219], v[22:25]
	v_mfma_f32_16x16x32_bf16 v[18:21], v[154:157], v[216:219], v[18:21]
	v_mfma_f32_16x16x32_bf16 v[30:33], v[146:149], v[224:227], v[30:33]
	v_mfma_f32_16x16x32_bf16 v[26:29], v[154:157], v[224:227], v[26:29]
	v_mfma_f32_16x16x32_bf16 v[6:9], v[150:153], v[204:207], v[6:9]
	v_mfma_f32_16x16x32_bf16 v[2:5], v[158:161], v[204:207], v[2:5]
	s_setprio 3
	s_barrier
	v_mfma_f32_16x16x32_bf16 v[14:17], v[150:153], v[212:215], v[14:17]
	v_mfma_f32_16x16x32_bf16 v[10:13], v[158:161], v[212:215], v[10:13]
	v_mfma_f32_16x16x32_bf16 v[22:25], v[150:153], v[220:223], v[22:25]
	v_mfma_f32_16x16x32_bf16 v[18:21], v[158:161], v[220:223], v[18:21]
	v_mfma_f32_16x16x32_bf16 v[30:33], v[150:153], v[228:231], v[30:33]
	v_mfma_f32_16x16x32_bf16 v[26:29], v[158:161], v[228:231], v[26:29]
	s_setprio 0
	s_add_i32 s96, 0, 0x18000
	s_add_i32 s97, 0, 0x1c000
	v_add_u32_e32 v142, s96, v173
	v_add_u32_e32 v158, s97, v173
	ds_read_b128 v[130:133], v142
	ds_read_b128 v[134:137], v142 offset:1024
	ds_read_b128 v[138:141], v142 offset:2048
	ds_read_b128 v[142:145], v142 offset:3072
	ds_read_b128 v[146:149], v158
	ds_read_b128 v[150:153], v158 offset:1024
	ds_read_b128 v[154:157], v158 offset:2048
	ds_read_b128 v[158:161], v158 offset:3072
	s_add_u32 s74, s74, 0x100000
	s_addc_u32 s75, s75, 0
	s_mov_b32 m0, s80
	v_lshl_add_u64 v[238:239], s[74:75], 0, v[162:163]
	ds_read_b128 v[200:203], v199 offset:32768
	ds_read_b128 v[204:207], v199 offset:33792
	ds_read_b128 v[208:211], v199 offset:34816
	ds_read_b128 v[212:215], v199 offset:35840
	ds_read_b128 v[216:219], v199 offset:36864
	ds_read_b128 v[220:223], v199 offset:37888
	ds_read_b128 v[224:227], v199 offset:38912
	ds_read_b128 v[228:231], v199 offset:39936
	global_load_lds_dwordx4 v[238:239], off
	v_lshl_add_u64 v[238:239], s[74:75], 0, v[166:167]
	s_mov_b32 m0, s81
	s_nop 0
	global_load_lds_dwordx4 v[238:239], off
	s_waitcnt vmcnt(8)
	s_waitcnt lgkmcnt(0)
	s_barrier
	s_setprio 1
	s_waitcnt lgkmcnt(0)
	v_mfma_f32_16x16x32_bf16 v[102:105], v[130:133], v[200:203], v[102:105]
	v_mfma_f32_16x16x32_bf16 v[98:101], v[138:141], v[200:203], v[98:101]
	v_mfma_f32_16x16x32_bf16 v[110:113], v[130:133], v[208:211], v[110:113]
	v_mfma_f32_16x16x32_bf16 v[106:109], v[138:141], v[208:211], v[106:109]
	v_mfma_f32_16x16x32_bf16 v[118:121], v[130:133], v[216:219], v[118:121]
	v_mfma_f32_16x16x32_bf16 v[114:117], v[138:141], v[216:219], v[114:117]
	v_mfma_f32_16x16x32_bf16 v[126:129], v[130:133], v[224:227], v[126:129]
	v_mfma_f32_16x16x32_bf16 v[122:125], v[138:141], v[224:227], v[122:125]
	v_mfma_f32_16x16x32_bf16 v[102:105], v[134:137], v[204:207], v[102:105]
	v_mfma_f32_16x16x32_bf16 v[98:101], v[142:145], v[204:207], v[98:101]
	v_mfma_f32_16x16x32_bf16 v[110:113], v[134:137], v[212:215], v[110:113]
	v_mfma_f32_16x16x32_bf16 v[106:109], v[142:145], v[212:215], v[106:109]
	v_mfma_f32_16x16x32_bf16 v[118:121], v[134:137], v[220:223], v[118:121]
	v_mfma_f32_16x16x32_bf16 v[114:117], v[142:145], v[220:223], v[114:117]
	v_mfma_f32_16x16x32_bf16 v[126:129], v[134:137], v[228:231], v[126:129]
	v_mfma_f32_16x16x32_bf16 v[122:125], v[142:145], v[228:231], v[122:125]
	s_setprio 0
	s_setprio 1
	v_mfma_f32_16x16x32_bf16 v[38:41], v[146:149], v[200:203], v[38:41]
	v_mfma_f32_16x16x32_bf16 v[34:37], v[154:157], v[200:203], v[34:37]
	v_mfma_f32_16x16x32_bf16 v[46:49], v[146:149], v[208:211], v[46:49]
	v_mfma_f32_16x16x32_bf16 v[42:45], v[154:157], v[208:211], v[42:45]
	v_mfma_f32_16x16x32_bf16 v[54:57], v[146:149], v[216:219], v[54:57]
	v_mfma_f32_16x16x32_bf16 v[50:53], v[154:157], v[216:219], v[50:53]
	v_mfma_f32_16x16x32_bf16 v[62:65], v[146:149], v[224:227], v[62:65]
	v_mfma_f32_16x16x32_bf16 v[58:61], v[154:157], v[224:227], v[58:61]
	v_mfma_f32_16x16x32_bf16 v[38:41], v[150:153], v[204:207], v[38:41]
	v_mfma_f32_16x16x32_bf16 v[34:37], v[158:161], v[204:207], v[34:37]
	v_mfma_f32_16x16x32_bf16 v[46:49], v[150:153], v[212:215], v[46:49]
	v_mfma_f32_16x16x32_bf16 v[42:45], v[158:161], v[212:215], v[42:45]
	v_mfma_f32_16x16x32_bf16 v[54:57], v[150:153], v[220:223], v[54:57]
	v_mfma_f32_16x16x32_bf16 v[50:53], v[158:161], v[220:223], v[50:53]
	s_setprio 3
	s_barrier
	v_mfma_f32_16x16x32_bf16 v[62:65], v[150:153], v[228:231], v[62:65]
	v_mfma_f32_16x16x32_bf16 v[58:61], v[158:161], v[228:231], v[58:61]
	s_setprio 0
	s_add_i32 s74, s96, s77
	v_lshl_add_u64 v[184:185], v[184:185], 0, s[38:39]
	s_mov_b32 m0, s74
	ds_read_b128 v[200:203], v199 offset:49152
	ds_read_b128 v[204:207], v199 offset:50176
	ds_read_b128 v[208:211], v199 offset:51200
	ds_read_b128 v[212:215], v199 offset:52224
	ds_read_b128 v[216:219], v199 offset:53248
	ds_read_b128 v[220:223], v199 offset:54272
	ds_read_b128 v[224:227], v199 offset:55296
	ds_read_b128 v[228:231], v199 offset:56320
	global_load_lds_dwordx4 v[184:185], off
	s_add_i32 m0, s74, 0x2000
	s_add_u32 s72, s72, 0x100080
	v_lshl_add_u64 v[184:185], v[232:233], 0, s[38:39]
	s_addc_u32 s73, s73, 0
	s_add_i32 s74, s97, s77
	global_load_lds_dwordx4 v[184:185], off
	v_lshl_add_u64 v[184:185], s[72:73], 0, v[164:165]
	s_mov_b32 m0, s74
	s_nop 0
	global_load_lds_dwordx4 v[184:185], off
	v_lshl_add_u64 v[184:185], s[72:73], 0, v[168:169]
	s_add_i32 m0, s74, 0x2000
	s_nop 0
	global_load_lds_dwordx4 v[184:185], off
	v_lshl_add_u64 v[184:185], v[234:235], 0, s[38:39]
	s_mov_b32 m0, s85
	s_nop 0
	global_load_lds_dwordx4 v[184:185], off
	v_lshl_add_u64 v[184:185], v[236:237], 0, s[38:39]
	s_mov_b32 m0, s86
	s_nop 0
	global_load_lds_dwordx4 v[184:185], off
	s_waitcnt vmcnt(8)
	s_waitcnt lgkmcnt(0)
	s_barrier
	s_setprio 1
	s_waitcnt lgkmcnt(0)
	v_mfma_f32_16x16x32_bf16 v[70:73], v[130:133], v[200:203], v[70:73]
	v_mfma_f32_16x16x32_bf16 v[66:69], v[138:141], v[200:203], v[66:69]
	v_mfma_f32_16x16x32_bf16 v[78:81], v[130:133], v[208:211], v[78:81]
	v_mfma_f32_16x16x32_bf16 v[74:77], v[138:141], v[208:211], v[74:77]
	v_mfma_f32_16x16x32_bf16 v[86:89], v[130:133], v[216:219], v[86:89]
	v_mfma_f32_16x16x32_bf16 v[82:85], v[138:141], v[216:219], v[82:85]
	v_mfma_f32_16x16x32_bf16 v[94:97], v[130:133], v[224:227], v[94:97]
	v_mfma_f32_16x16x32_bf16 v[90:93], v[138:141], v[224:227], v[90:93]
	v_mfma_f32_16x16x32_bf16 v[70:73], v[134:137], v[204:207], v[70:73]
	v_mfma_f32_16x16x32_bf16 v[66:69], v[142:145], v[204:207], v[66:69]
	v_mfma_f32_16x16x32_bf16 v[78:81], v[134:137], v[212:215], v[78:81]
	v_mfma_f32_16x16x32_bf16 v[74:77], v[142:145], v[212:215], v[74:77]
	v_mfma_f32_16x16x32_bf16 v[86:89], v[134:137], v[220:223], v[86:89]
	v_mfma_f32_16x16x32_bf16 v[82:85], v[142:145], v[220:223], v[82:85]
	v_mfma_f32_16x16x32_bf16 v[94:97], v[134:137], v[228:231], v[94:97]
	v_mfma_f32_16x16x32_bf16 v[90:93], v[142:145], v[228:231], v[90:93]
	s_setprio 0
	s_setprio 1
	v_mfma_f32_16x16x32_bf16 v[6:9], v[146:149], v[200:203], v[6:9]
	v_mfma_f32_16x16x32_bf16 v[2:5], v[154:157], v[200:203], v[2:5]
	v_mfma_f32_16x16x32_bf16 v[14:17], v[146:149], v[208:211], v[14:17]
	v_mfma_f32_16x16x32_bf16 v[10:13], v[154:157], v[208:211], v[10:13]
	v_mfma_f32_16x16x32_bf16 v[22:25], v[146:149], v[216:219], v[22:25]
	v_mfma_f32_16x16x32_bf16 v[18:21], v[154:157], v[216:219], v[18:21]
	v_mfma_f32_16x16x32_bf16 v[30:33], v[146:149], v[224:227], v[30:33]
	v_mfma_f32_16x16x32_bf16 v[26:29], v[154:157], v[224:227], v[26:29]
	v_mfma_f32_16x16x32_bf16 v[6:9], v[150:153], v[204:207], v[6:9]
	v_mfma_f32_16x16x32_bf16 v[2:5], v[158:161], v[204:207], v[2:5]
	s_setprio 3
	s_barrier
	v_mfma_f32_16x16x32_bf16 v[14:17], v[150:153], v[212:215], v[14:17]
	v_mfma_f32_16x16x32_bf16 v[10:13], v[158:161], v[212:215], v[10:13]
	v_mfma_f32_16x16x32_bf16 v[22:25], v[150:153], v[220:223], v[22:25]
	v_mfma_f32_16x16x32_bf16 v[18:21], v[158:161], v[220:223], v[18:21]
	v_mfma_f32_16x16x32_bf16 v[30:33], v[150:153], v[228:231], v[30:33]
	v_mfma_f32_16x16x32_bf16 v[26:29], v[158:161], v[228:231], v[26:29]
	s_setprio 0
	s_add_i32 s95, s95, 2
	s_add_u32 s70, s70, 0x100
	s_addc_u32 s71, s71, 0
	s_add_u32 s93, s93, 0x100
	s_addc_u32 s94, s94, 0
	s_cmp_gt_u32 s95, 61
	s_cbranch_scc0 .LBB0_743
	s_and_b64 vcc, exec, s[40:41]
	s_cbranch_vccz .LBB0_746
	s_barrier

.LBB0_902:
	ds_read_b128 v[144:147], v155
	ds_read_b128 v[148:151], v155 offset:1024
	ds_read_b128 v[158:161], v155 offset:2048
	ds_read_b128 v[162:165], v155 offset:3072
	ds_read_b128 v[166:169], v156
	ds_read_b128 v[170:173], v156 offset:1024
	ds_read_b128 v[174:177], v156 offset:2048
	ds_read_b128 v[178:181], v156 offset:3072
	s_add_u32 s50, s48, 0x100
	s_addc_u32 s51, s49, 0
	s_cmpk_eq_i32 s73, 0xa8
	s_cselect_b32 s55, s9, s51
	s_cselect_b32 s54, s8, s50
	s_cselect_b32 s53, s47, s72
	s_cselect_b32 s52, s46, s71
	v_lshl_add_u64 v[214:215], s[48:49], 0, v[136:137]
	s_add_i32 m0, s57, 0xc000
	ds_read_b128 v[182:185], v157
	ds_read_b128 v[186:189], v157 offset:1024
	ds_read_b128 v[190:193], v157 offset:2048
	ds_read_b128 v[194:197], v157 offset:3072
	ds_read_b128 v[198:201], v157 offset:4096
	ds_read_b128 v[202:205], v157 offset:5120
	ds_read_b128 v[206:209], v157 offset:6144
	ds_read_b128 v[210:213], v157 offset:7168
	global_load_lds_dwordx4 v[214:215], off
	v_lshl_add_u64 v[214:215], s[48:49], 0, v[138:139]
	s_add_i32 m0, s57, 0xe000
	s_nop 0
	global_load_lds_dwordx4 v[214:215], off
	s_waitcnt vmcnt(8)
	s_waitcnt lgkmcnt(0)
	s_barrier
	s_setprio 1
	s_waitcnt lgkmcnt(0)
	v_mfma_f32_16x16x32_bf16 v[124:127], v[144:147], v[182:185], v[124:127]
	v_mfma_f32_16x16x32_bf16 v[120:123], v[158:161], v[182:185], v[120:123]
	v_mfma_f32_16x16x32_bf16 v[116:119], v[144:147], v[190:193], v[116:119]
	v_mfma_f32_16x16x32_bf16 v[112:115], v[158:161], v[190:193], v[112:115]
	v_mfma_f32_16x16x32_bf16 v[92:95], v[144:147], v[198:201], v[92:95]
	v_mfma_f32_16x16x32_bf16 v[88:91], v[158:161], v[198:201], v[88:91]
	v_mfma_f32_16x16x32_bf16 v[76:79], v[144:147], v[206:209], v[76:79]
	v_mfma_f32_16x16x32_bf16 v[72:75], v[158:161], v[206:209], v[72:75]
	v_mfma_f32_16x16x32_bf16 v[124:127], v[148:151], v[186:189], v[124:127]
	v_mfma_f32_16x16x32_bf16 v[120:123], v[162:165], v[186:189], v[120:123]
	v_mfma_f32_16x16x32_bf16 v[116:119], v[148:151], v[194:197], v[116:119]
	v_mfma_f32_16x16x32_bf16 v[112:115], v[162:165], v[194:197], v[112:115]
	v_mfma_f32_16x16x32_bf16 v[92:95], v[148:151], v[202:205], v[92:95]
	v_mfma_f32_16x16x32_bf16 v[88:91], v[162:165], v[202:205], v[88:91]
	v_mfma_f32_16x16x32_bf16 v[76:79], v[148:151], v[210:213], v[76:79]
	v_mfma_f32_16x16x32_bf16 v[72:75], v[162:165], v[210:213], v[72:75]
	s_setprio 0
	s_setprio 1
	v_mfma_f32_16x16x32_bf16 v[108:111], v[166:169], v[182:185], v[108:111]
	v_mfma_f32_16x16x32_bf16 v[104:107], v[174:177], v[182:185], v[104:107]
	v_mfma_f32_16x16x32_bf16 v[100:103], v[166:169], v[190:193], v[100:103]
	v_mfma_f32_16x16x32_bf16 v[96:99], v[174:177], v[190:193], v[96:99]
	v_mfma_f32_16x16x32_bf16 v[84:87], v[166:169], v[198:201], v[84:87]
	v_mfma_f32_16x16x32_bf16 v[80:83], v[174:177], v[198:201], v[80:83]
	v_mfma_f32_16x16x32_bf16 v[68:71], v[166:169], v[206:209], v[68:71]
	v_mfma_f32_16x16x32_bf16 v[64:67], v[174:177], v[206:209], v[64:67]
	v_mfma_f32_16x16x32_bf16 v[108:111], v[170:173], v[186:189], v[108:111]
	v_mfma_f32_16x16x32_bf16 v[104:107], v[178:181], v[186:189], v[104:107]
	v_mfma_f32_16x16x32_bf16 v[100:103], v[170:173], v[194:197], v[100:103]
	v_mfma_f32_16x16x32_bf16 v[96:99], v[178:181], v[194:197], v[96:99]
	v_mfma_f32_16x16x32_bf16 v[84:87], v[170:173], v[202:205], v[84:87]
	v_mfma_f32_16x16x32_bf16 v[80:83], v[178:181], v[202:205], v[80:83]
	s_setprio 3
	s_barrier
	v_mfma_f32_16x16x32_bf16 v[68:71], v[170:173], v[210:213], v[68:71]
	v_mfma_f32_16x16x32_bf16 v[64:67], v[178:181], v[210:213], v[64:67]
	s_setprio 0
	s_add_i32 s48, s65, s56
	v_lshl_add_u64 v[214:215], s[52:53], 0, v[130:131]
	s_mov_b32 m0, s48
	ds_read_b128 v[182:185], v157 offset:16384
	ds_read_b128 v[186:189], v157 offset:17408
	ds_read_b128 v[190:193], v157 offset:18432
	ds_read_b128 v[194:197], v157 offset:19456
	ds_read_b128 v[198:201], v157 offset:20480
	ds_read_b128 v[202:205], v157 offset:21504
	ds_read_b128 v[206:209], v157 offset:22528
	ds_read_b128 v[210:213], v157 offset:23552
	global_load_lds_dwordx4 v[214:215], off
	s_add_i32 m0, s48, 0x2000
	s_add_u32 s48, s52, 0x2b0000
	v_lshl_add_u64 v[216:217], s[52:53], 0, v[134:135]
	s_addc_u32 s49, s53, 0
	s_add_i32 s74, s66, s56
	global_load_lds_dwordx4 v[216:217], off
	v_lshl_add_u64 v[218:219], s[48:49], 0, v[130:131]
	s_mov_b32 m0, s74
	v_lshl_add_u64 v[220:221], s[54:55], 0, v[132:133]
	global_load_lds_dwordx4 v[218:219], off
	v_lshl_add_u64 v[218:219], s[48:49], 0, v[134:135]
	s_add_i32 m0, s74, 0x2000
	s_nop 0
	global_load_lds_dwordx4 v[218:219], off
	v_lshl_add_u64 v[218:219], s[54:55], 0, v[128:129]
	s_mov_b32 m0, s57
	s_nop 0
	global_load_lds_dwordx4 v[218:219], off
	s_mov_b32 m0, s58
	s_nop 0
	global_load_lds_dwordx4 v[220:221], off
	s_waitcnt vmcnt(8)
	s_waitcnt lgkmcnt(0)
	s_barrier
	s_setprio 1
	s_waitcnt lgkmcnt(0)
	v_mfma_f32_16x16x32_bf16 v[60:63], v[144:147], v[182:185], v[60:63]
	v_mfma_f32_16x16x32_bf16 v[56:59], v[158:161], v[182:185], v[56:59]
	v_mfma_f32_16x16x32_bf16 v[44:47], v[144:147], v[190:193], v[44:47]
	v_mfma_f32_16x16x32_bf16 v[40:43], v[158:161], v[190:193], v[40:43]
	v_mfma_f32_16x16x32_bf16 v[28:31], v[144:147], v[198:201], v[28:31]
	v_mfma_f32_16x16x32_bf16 v[24:27], v[158:161], v[198:201], v[24:27]
	v_mfma_f32_16x16x32_bf16 v[12:15], v[144:147], v[206:209], v[12:15]
	v_mfma_f32_16x16x32_bf16 v[8:11], v[158:161], v[206:209], v[8:11]
	v_mfma_f32_16x16x32_bf16 v[60:63], v[148:151], v[186:189], v[60:63]
	v_mfma_f32_16x16x32_bf16 v[56:59], v[162:165], v[186:189], v[56:59]
	v_mfma_f32_16x16x32_bf16 v[44:47], v[148:151], v[194:197], v[44:47]
	v_mfma_f32_16x16x32_bf16 v[40:43], v[162:165], v[194:197], v[40:43]
	v_mfma_f32_16x16x32_bf16 v[28:31], v[148:151], v[202:205], v[28:31]
	v_mfma_f32_16x16x32_bf16 v[24:27], v[162:165], v[202:205], v[24:27]
	v_mfma_f32_16x16x32_bf16 v[12:15], v[148:151], v[210:213], v[12:15]
	v_mfma_f32_16x16x32_bf16 v[8:11], v[162:165], v[210:213], v[8:11]
	s_setprio 0
	s_setprio 1
	v_mfma_f32_16x16x32_bf16 v[52:55], v[166:169], v[182:185], v[52:55]
	v_mfma_f32_16x16x32_bf16 v[48:51], v[174:177], v[182:185], v[48:51]
	v_mfma_f32_16x16x32_bf16 v[36:39], v[166:169], v[190:193], v[36:39]
	v_mfma_f32_16x16x32_bf16 v[32:35], v[174:177], v[190:193], v[32:35]
	v_mfma_f32_16x16x32_bf16 v[20:23], v[166:169], v[198:201], v[20:23]
	v_mfma_f32_16x16x32_bf16 v[16:19], v[174:177], v[198:201], v[16:19]
	v_mfma_f32_16x16x32_bf16 v[4:7], v[166:169], v[206:209], v[4:7]
	v_mfma_f32_16x16x32_bf16 v[0:3], v[174:177], v[206:209], v[0:3]
	v_mfma_f32_16x16x32_bf16 v[52:55], v[170:173], v[186:189], v[52:55]
	v_mfma_f32_16x16x32_bf16 v[48:51], v[178:181], v[186:189], v[48:51]
	s_setprio 3
	s_barrier
	v_mfma_f32_16x16x32_bf16 v[36:39], v[170:173], v[194:197], v[36:39]
	v_mfma_f32_16x16x32_bf16 v[32:35], v[178:181], v[194:197], v[32:35]
	v_mfma_f32_16x16x32_bf16 v[20:23], v[170:173], v[202:205], v[20:23]
	v_mfma_f32_16x16x32_bf16 v[16:19], v[178:181], v[202:205], v[16:19]
	v_mfma_f32_16x16x32_bf16 v[4:7], v[170:173], v[210:213], v[4:7]
	v_mfma_f32_16x16x32_bf16 v[0:3], v[178:181], v[210:213], v[0:3]
	s_setprio 0
	s_add_i32 s74, 0, 0x18000
	s_add_i32 s75, 0, 0x1c000
	v_add_u32_e32 v162, s74, v153
	v_add_u32_e32 v178, s75, v153
	ds_read_b128 v[144:147], v162
	ds_read_b128 v[148:151], v162 offset:1024
	ds_read_b128 v[158:161], v162 offset:2048
	ds_read_b128 v[162:165], v162 offset:3072
	ds_read_b128 v[166:169], v178
	ds_read_b128 v[170:173], v178 offset:1024
	ds_read_b128 v[174:177], v178 offset:2048
	ds_read_b128 v[178:181], v178 offset:3072
	s_add_u32 s48, s54, 0x2b0000
	s_addc_u32 s49, s55, 0
	s_mov_b32 m0, s59
	v_lshl_add_u64 v[222:223], s[48:49], 0, v[128:129]
	ds_read_b128 v[182:185], v157 offset:32768
	ds_read_b128 v[186:189], v157 offset:33792
	ds_read_b128 v[190:193], v157 offset:34816
	ds_read_b128 v[194:197], v157 offset:35840
	ds_read_b128 v[198:201], v157 offset:36864
	ds_read_b128 v[202:205], v157 offset:37888
	ds_read_b128 v[206:209], v157 offset:38912
	ds_read_b128 v[210:213], v157 offset:39936
	global_load_lds_dwordx4 v[222:223], off
	v_lshl_add_u64 v[222:223], s[48:49], 0, v[132:133]
	s_mov_b32 m0, s60
	s_nop 0
	global_load_lds_dwordx4 v[222:223], off
	s_waitcnt vmcnt(8)
	s_waitcnt lgkmcnt(0)
	s_barrier
	s_setprio 1
	s_waitcnt lgkmcnt(0)
	v_mfma_f32_16x16x32_bf16 v[124:127], v[144:147], v[182:185], v[124:127]
	v_mfma_f32_16x16x32_bf16 v[120:123], v[158:161], v[182:185], v[120:123]
	v_mfma_f32_16x16x32_bf16 v[116:119], v[144:147], v[190:193], v[116:119]
	v_mfma_f32_16x16x32_bf16 v[112:115], v[158:161], v[190:193], v[112:115]
	v_mfma_f32_16x16x32_bf16 v[92:95], v[144:147], v[198:201], v[92:95]
	v_mfma_f32_16x16x32_bf16 v[88:91], v[158:161], v[198:201], v[88:91]
	v_mfma_f32_16x16x32_bf16 v[76:79], v[144:147], v[206:209], v[76:79]
	v_mfma_f32_16x16x32_bf16 v[72:75], v[158:161], v[206:209], v[72:75]
	v_mfma_f32_16x16x32_bf16 v[124:127], v[148:151], v[186:189], v[124:127]
	v_mfma_f32_16x16x32_bf16 v[120:123], v[162:165], v[186:189], v[120:123]
	v_mfma_f32_16x16x32_bf16 v[116:119], v[148:151], v[194:197], v[116:119]
	v_mfma_f32_16x16x32_bf16 v[112:115], v[162:165], v[194:197], v[112:115]
	v_mfma_f32_16x16x32_bf16 v[92:95], v[148:151], v[202:205], v[92:95]
	v_mfma_f32_16x16x32_bf16 v[88:91], v[162:165], v[202:205], v[88:91]
	v_mfma_f32_16x16x32_bf16 v[76:79], v[148:151], v[210:213], v[76:79]
	v_mfma_f32_16x16x32_bf16 v[72:75], v[162:165], v[210:213], v[72:75]
	s_setprio 0
	s_setprio 1
	v_mfma_f32_16x16x32_bf16 v[108:111], v[166:169], v[182:185], v[108:111]
	v_mfma_f32_16x16x32_bf16 v[104:107], v[174:177], v[182:185], v[104:107]
	v_mfma_f32_16x16x32_bf16 v[100:103], v[166:169], v[190:193], v[100:103]
	v_mfma_f32_16x16x32_bf16 v[96:99], v[174:177], v[190:193], v[96:99]
	v_mfma_f32_16x16x32_bf16 v[84:87], v[166:169], v[198:201], v[84:87]
	v_mfma_f32_16x16x32_bf16 v[80:83], v[174:177], v[198:201], v[80:83]
	v_mfma_f32_16x16x32_bf16 v[68:71], v[166:169], v[206:209], v[68:71]
	v_mfma_f32_16x16x32_bf16 v[64:67], v[174:177], v[206:209], v[64:67]
	v_mfma_f32_16x16x32_bf16 v[108:111], v[170:173], v[186:189], v[108:111]
	v_mfma_f32_16x16x32_bf16 v[104:107], v[178:181], v[186:189], v[104:107]
	v_mfma_f32_16x16x32_bf16 v[100:103], v[170:173], v[194:197], v[100:103]
	v_mfma_f32_16x16x32_bf16 v[96:99], v[178:181], v[194:197], v[96:99]
	v_mfma_f32_16x16x32_bf16 v[84:87], v[170:173], v[202:205], v[84:87]
	v_mfma_f32_16x16x32_bf16 v[80:83], v[178:181], v[202:205], v[80:83]
	s_setprio 3
	s_barrier
	v_mfma_f32_16x16x32_bf16 v[68:71], v[170:173], v[210:213], v[68:71]
	v_mfma_f32_16x16x32_bf16 v[64:67], v[178:181], v[210:213], v[64:67]
	s_setprio 0
	s_add_i32 s48, s74, s56
	v_lshl_add_u64 v[214:215], v[214:215], 0, s[30:31]
	s_mov_b32 m0, s48
	ds_read_b128 v[182:185], v157 offset:49152
	ds_read_b128 v[186:189], v157 offset:50176
	ds_read_b128 v[190:193], v157 offset:51200
	ds_read_b128 v[194:197], v157 offset:52224
	ds_read_b128 v[198:201], v157 offset:53248
	ds_read_b128 v[202:205], v157 offset:54272
	ds_read_b128 v[206:209], v157 offset:55296
	ds_read_b128 v[210:213], v157 offset:56320
	global_load_lds_dwordx4 v[214:215], off
	s_add_i32 m0, s48, 0x2000
	s_add_u32 s48, s52, 0x2b0080
	v_lshl_add_u64 v[214:215], v[216:217], 0, s[30:31]
	s_addc_u32 s49, s53, 0
	s_add_i32 s52, s75, s56
	global_load_lds_dwordx4 v[214:215], off
	v_lshl_add_u64 v[214:215], s[48:49], 0, v[130:131]
	s_mov_b32 m0, s52
	s_nop 0
	global_load_lds_dwordx4 v[214:215], off
	v_lshl_add_u64 v[214:215], s[48:49], 0, v[134:135]
	s_add_i32 m0, s52, 0x2000
	s_nop 0
	global_load_lds_dwordx4 v[214:215], off
	v_lshl_add_u64 v[214:215], v[218:219], 0, s[30:31]
	s_mov_b32 m0, s62
	s_nop 0
	global_load_lds_dwordx4 v[214:215], off
	v_lshl_add_u64 v[214:215], v[220:221], 0, s[30:31]
	s_mov_b32 m0, s63
	s_nop 0
	global_load_lds_dwordx4 v[214:215], off
	s_waitcnt vmcnt(8)
	s_waitcnt lgkmcnt(0)
	s_barrier
	s_setprio 1
	s_waitcnt lgkmcnt(0)
	v_mfma_f32_16x16x32_bf16 v[60:63], v[144:147], v[182:185], v[60:63]
	v_mfma_f32_16x16x32_bf16 v[56:59], v[158:161], v[182:185], v[56:59]
	v_mfma_f32_16x16x32_bf16 v[44:47], v[144:147], v[190:193], v[44:47]
	v_mfma_f32_16x16x32_bf16 v[40:43], v[158:161], v[190:193], v[40:43]
	v_mfma_f32_16x16x32_bf16 v[28:31], v[144:147], v[198:201], v[28:31]
	v_mfma_f32_16x16x32_bf16 v[24:27], v[158:161], v[198:201], v[24:27]
	v_mfma_f32_16x16x32_bf16 v[12:15], v[144:147], v[206:209], v[12:15]
	v_mfma_f32_16x16x32_bf16 v[8:11], v[158:161], v[206:209], v[8:11]
	v_mfma_f32_16x16x32_bf16 v[60:63], v[148:151], v[186:189], v[60:63]
	v_mfma_f32_16x16x32_bf16 v[56:59], v[162:165], v[186:189], v[56:59]
	v_mfma_f32_16x16x32_bf16 v[44:47], v[148:151], v[194:197], v[44:47]
	v_mfma_f32_16x16x32_bf16 v[40:43], v[162:165], v[194:197], v[40:43]
	v_mfma_f32_16x16x32_bf16 v[28:31], v[148:151], v[202:205], v[28:31]
	v_mfma_f32_16x16x32_bf16 v[24:27], v[162:165], v[202:205], v[24:27]
	v_mfma_f32_16x16x32_bf16 v[12:15], v[148:151], v[210:213], v[12:15]
	v_mfma_f32_16x16x32_bf16 v[8:11], v[162:165], v[210:213], v[8:11]
	s_setprio 0
	s_setprio 1
	v_mfma_f32_16x16x32_bf16 v[52:55], v[166:169], v[182:185], v[52:55]
	v_mfma_f32_16x16x32_bf16 v[48:51], v[174:177], v[182:185], v[48:51]
	v_mfma_f32_16x16x32_bf16 v[36:39], v[166:169], v[190:193], v[36:39]
	v_mfma_f32_16x16x32_bf16 v[32:35], v[174:177], v[190:193], v[32:35]
	v_mfma_f32_16x16x32_bf16 v[20:23], v[166:169], v[198:201], v[20:23]
	v_mfma_f32_16x16x32_bf16 v[16:19], v[174:177], v[198:201], v[16:19]
	v_mfma_f32_16x16x32_bf16 v[4:7], v[166:169], v[206:209], v[4:7]
	v_mfma_f32_16x16x32_bf16 v[0:3], v[174:177], v[206:209], v[0:3]
	v_mfma_f32_16x16x32_bf16 v[52:55], v[170:173], v[186:189], v[52:55]
	v_mfma_f32_16x16x32_bf16 v[48:51], v[178:181], v[186:189], v[48:51]
	s_setprio 3
	s_barrier
	v_mfma_f32_16x16x32_bf16 v[36:39], v[170:173], v[194:197], v[36:39]
	v_mfma_f32_16x16x32_bf16 v[32:35], v[178:181], v[194:197], v[32:35]
	v_mfma_f32_16x16x32_bf16 v[20:23], v[170:173], v[202:205], v[20:23]
	v_mfma_f32_16x16x32_bf16 v[16:19], v[178:181], v[202:205], v[16:19]
	v_mfma_f32_16x16x32_bf16 v[4:7], v[170:173], v[210:213], v[4:7]
	v_mfma_f32_16x16x32_bf16 v[0:3], v[178:181], v[210:213], v[0:3]
	s_setprio 0
	s_add_i32 s73, s73, 2
	s_add_u32 s71, s71, 0x100
	s_addc_u32 s72, s72, 0
	s_cmpk_gt_u32 s73, 0xa9
	s_mov_b64 s[48:49], s[50:51]
	s_cbranch_scc0 .LBB0_902
	s_and_b64 vcc, exec, s[34:35]
	s_cbranch_vccz .LBB0_905
	s_barrier
